# k22
# speedup vs baseline: 1.0051x; 1.0021x over previous
; #define PG8_STAGE(bufoff, gbase, voff) do { _Pragma("unroll") for (int _i = 0; _i < 2; ++_i) \
;         __builtin_amdgcn_global_load_lds((const unsigned*)((const char*)(gbase) + (voff)[_i]), (LAS unsigned*)(lds + (bufoff) + ldsw + _i * 8192), 16, 0, 0); } while (0)
; #define PG8_LDA(dst, b, h) do { _Pragma("unroll") for (int m = 0; m < 4; ++m) _Pragma("unroll") for (int k = 0; k < 2; ++k) dst[m][k] = *(const LAS bf16x8*)(lds + PG8_SA(b, h) + aoff + m * 2048 + k * 1024); } while (0)
; #define PG8_LDB(dst, b, h) do { _Pragma("unroll") for (int n = 0; n < 2; ++n) _Pragma("unroll") for (int k = 0; k < 2; ++k) dst[n][k] = *(const LAS bf16x8*)(lds + PG8_SB(b, h) + boff + n * 2048 + k * 1024); } while (0)
; #define PG8_MMA(ai, bj, At, Bt) do { __builtin_amdgcn_s_setprio(1); _Pragma("unroll") for (int m = 0; m < 4; ++m) _Pragma("unroll") for (int n = 0; n < 2; ++n) _Pragma("unroll") for (int k = 0; k < 2; ++k) \
;         acc[ai][bj][m][n] = __builtin_amdgcn_mfma_f32_16x16x32_bf16(Bt[n][k], At[m][k], acc[ai][bj][m][n], 0, 0, 0); __builtin_amdgcn_s_setprio(0); } while (0)
; #define PG8_WAIT_V(n) asm volatile("s_waitcnt vmcnt(" #n ")" ::: "memory")
; #define PG8_WAIT_L(n) asm volatile("s_waitcnt lgkmcnt(" #n ")" ::: "memory")
; #define PG8_BAR __builtin_amdgcn_s_barrier()
; #define PG8_SCHED __builtin_amdgcn_sched_barrier(0)
; template <class Epi, class Sched>
; __device__ __forceinline__ void gemm_phase(LAS unsigned char* lds, const Gemm g, const Sched& S, const Epi& E, int wid_) {
;     ...
;             PG8_LDB(B0, 0, 0); PG8_LDB(B1, 0, 1); PG8_SCHED; PG8_LDA(At, 0, 0); PG8_STAGE(PG8_SA(1, 1), a1 + hstepA, voffA);
;             PG8_WAIT_V(8); PG8_WAIT_L(0); PG8_BAR; PG8_MMA(0, 0, At, B0); PG8_MMA(0, 1, At, B1); PG8_BAR; PG8_SCHED;
;             PG8_LDA(At, 0, 1); PG8_STAGE(PG8_SB(0, 0), b2, voffB); PG8_STAGE(PG8_SB(0, 1), b2 + hstepB, voffB); PG8_STAGE(PG8_SA(0, 0), a2, voffA);
;             PG8_WAIT_V(8); PG8_WAIT_L(0); PG8_BAR; PG8_MMA(1, 0, At, B0); PG8_MMA(1, 1, At, B1); PG8_BAR; PG8_SCHED;
.LBB0_435:
	s_add_u32 s12, s38, 0xfffc0080
	s_addc_u32 s14, s39, -1
	s_add_i32 s34, 0, 0x10000
	s_cmp_eq_u32 s33, 12
	s_cselect_b32 s43, s16, s14
	s_cselect_b32 s42, s21, s12
	s_cselect_b32 s41, s23, s54
	s_cselect_b32 s40, s37, s83
	s_add_i32 s12, 0, 0x14000
	v_add_u32_e32 v142, s34, v182
	v_add_u32_e32 v168, s12, v182
	ds_read_b128 v[130:133], v142
	ds_read_b128 v[134:137], v142 offset:1024
	ds_read_b128 v[138:141], v142 offset:2048
	ds_read_b128 v[142:145], v142 offset:3072
	ds_read_b128 v[146:149], v168
	ds_read_b128 v[150:153], v168 offset:1024
	ds_read_b128 v[164:167], v168 offset:2048
	ds_read_b128 v[168:171], v168 offset:3072
	s_add_i32 m0, s48, 0xc000
	ds_read_b128 v[172:175], v183
	ds_read_b128 v[176:179], v183 offset:1024
	ds_read_b128 v[184:187], v183 offset:2048
	ds_read_b128 v[188:191], v183 offset:3072
	ds_read_b128 v[192:195], v183 offset:4096
	ds_read_b128 v[196:199], v183 offset:5120
	ds_read_b128 v[200:203], v183 offset:6144
	ds_read_b128 v[204:207], v183 offset:7168
	global_load_lds_dwordx4 v160, s[38:39]
	s_add_i32 m0, s48, 0xe000
	s_nop 0
	global_load_lds_dwordx4 v162, s[38:39]
	s_waitcnt vmcnt(8)
	s_waitcnt lgkmcnt(0)
	s_barrier
	s_setprio 1
	s_waitcnt lgkmcnt(0)
	v_mfma_f32_16x16x32_bf16 v[126:129], v[130:133], v[172:175], v[126:129]
	v_mfma_f32_16x16x32_bf16 v[122:125], v[138:141], v[172:175], v[122:125]
	v_mfma_f32_16x16x32_bf16 v[110:113], v[130:133], v[184:187], v[110:113]
	v_mfma_f32_16x16x32_bf16 v[106:109], v[138:141], v[184:187], v[106:109]
	v_mfma_f32_16x16x32_bf16 v[94:97], v[130:133], v[192:195], v[94:97]
	v_mfma_f32_16x16x32_bf16 v[90:93], v[138:141], v[192:195], v[90:93]
	v_mfma_f32_16x16x32_bf16 v[78:81], v[130:133], v[200:203], v[78:81]
	v_mfma_f32_16x16x32_bf16 v[74:77], v[138:141], v[200:203], v[74:77]
	v_mfma_f32_16x16x32_bf16 v[126:129], v[134:137], v[176:179], v[126:129]
	v_mfma_f32_16x16x32_bf16 v[122:125], v[142:145], v[176:179], v[122:125]
	v_mfma_f32_16x16x32_bf16 v[110:113], v[134:137], v[188:191], v[110:113]
	v_mfma_f32_16x16x32_bf16 v[106:109], v[142:145], v[188:191], v[106:109]
	v_mfma_f32_16x16x32_bf16 v[94:97], v[134:137], v[196:199], v[94:97]
	v_mfma_f32_16x16x32_bf16 v[90:93], v[142:145], v[196:199], v[90:93]
	v_mfma_f32_16x16x32_bf16 v[78:81], v[134:137], v[204:207], v[78:81]
	v_mfma_f32_16x16x32_bf16 v[74:77], v[142:145], v[204:207], v[74:77]
	s_setprio 0
	s_setprio 1
	v_mfma_f32_16x16x32_bf16 v[118:121], v[146:149], v[172:175], v[118:121]
	v_mfma_f32_16x16x32_bf16 v[114:117], v[164:167], v[172:175], v[114:117]
	v_mfma_f32_16x16x32_bf16 v[102:105], v[146:149], v[184:187], v[102:105]
	v_mfma_f32_16x16x32_bf16 v[98:101], v[164:167], v[184:187], v[98:101]
	v_mfma_f32_16x16x32_bf16 v[86:89], v[146:149], v[192:195], v[86:89]
	v_mfma_f32_16x16x32_bf16 v[82:85], v[164:167], v[192:195], v[82:85]
	v_mfma_f32_16x16x32_bf16 v[70:73], v[146:149], v[200:203], v[70:73]
	v_mfma_f32_16x16x32_bf16 v[66:69], v[164:167], v[200:203], v[66:69]
	v_mfma_f32_16x16x32_bf16 v[118:121], v[150:153], v[176:179], v[118:121]
	v_mfma_f32_16x16x32_bf16 v[114:117], v[168:171], v[176:179], v[114:117]
	v_mfma_f32_16x16x32_bf16 v[102:105], v[150:153], v[188:191], v[102:105]
	v_mfma_f32_16x16x32_bf16 v[98:101], v[168:171], v[188:191], v[98:101]
	v_mfma_f32_16x16x32_bf16 v[86:89], v[150:153], v[196:199], v[86:89]
	v_mfma_f32_16x16x32_bf16 v[82:85], v[168:171], v[196:199], v[82:85]
	v_mfma_f32_16x16x32_bf16 v[70:73], v[150:153], v[204:207], v[70:73]
	v_mfma_f32_16x16x32_bf16 v[66:69], v[168:171], v[204:207], v[66:69]
	s_setprio 0
	s_barrier
	s_add_i32 s14, s34, s46
	s_mov_b32 m0, s14
	ds_read_b128 v[172:175], v183 offset:16384
	ds_read_b128 v[176:179], v183 offset:17408
	ds_read_b128 v[184:187], v183 offset:18432
	ds_read_b128 v[188:191], v183 offset:19456
	ds_read_b128 v[192:195], v183 offset:20480
	ds_read_b128 v[196:199], v183 offset:21504
	ds_read_b128 v[200:203], v183 offset:22528
	ds_read_b128 v[204:207], v183 offset:23552
	global_load_lds_dwordx4 v0, s[40:41]
	s_add_i32 m0, s14, 0x2000
	s_add_u32 s34, s40, 0x40000
	s_addc_u32 s35, s41, 0
	s_add_i32 s12, s12, s46
	global_load_lds_dwordx4 v158, s[40:41]
	s_mov_b32 m0, s12
	s_nop 0
	global_load_lds_dwordx4 v0, s[34:35]
	s_add_i32 m0, s12, 0x2000
	s_nop 0
	global_load_lds_dwordx4 v158, s[34:35]
	s_mov_b32 m0, s48
	s_nop 0
	global_load_lds_dwordx4 v154, s[42:43]
	s_mov_b32 m0, s49
	s_nop 0
	global_load_lds_dwordx4 v156, s[42:43]
	s_waitcnt vmcnt(8)
	s_waitcnt lgkmcnt(0)
	s_barrier
	s_setprio 1
	s_waitcnt lgkmcnt(0)
	v_mfma_f32_16x16x32_bf16 v[62:65], v[130:133], v[172:175], v[62:65]
	v_mfma_f32_16x16x32_bf16 v[58:61], v[138:141], v[172:175], v[58:61]
	v_mfma_f32_16x16x32_bf16 v[46:49], v[130:133], v[184:187], v[46:49]
	v_mfma_f32_16x16x32_bf16 v[42:45], v[138:141], v[184:187], v[42:45]
	v_mfma_f32_16x16x32_bf16 v[30:33], v[130:133], v[192:195], v[30:33]
	v_mfma_f32_16x16x32_bf16 v[26:29], v[138:141], v[192:195], v[26:29]
	v_mfma_f32_16x16x32_bf16 v[14:17], v[130:133], v[200:203], v[14:17]
	v_mfma_f32_16x16x32_bf16 v[10:13], v[138:141], v[200:203], v[10:13]
	v_mfma_f32_16x16x32_bf16 v[62:65], v[134:137], v[176:179], v[62:65]
	v_mfma_f32_16x16x32_bf16 v[58:61], v[142:145], v[176:179], v[58:61]
	v_mfma_f32_16x16x32_bf16 v[46:49], v[134:137], v[188:191], v[46:49]
	v_mfma_f32_16x16x32_bf16 v[42:45], v[142:145], v[188:191], v[42:45]
	v_mfma_f32_16x16x32_bf16 v[30:33], v[134:137], v[196:199], v[30:33]
	v_mfma_f32_16x16x32_bf16 v[26:29], v[142:145], v[196:199], v[26:29]
	v_mfma_f32_16x16x32_bf16 v[14:17], v[134:137], v[204:207], v[14:17]
	v_mfma_f32_16x16x32_bf16 v[10:13], v[142:145], v[204:207], v[10:13]
	s_setprio 0
	s_setprio 1
	v_mfma_f32_16x16x32_bf16 v[54:57], v[146:149], v[172:175], v[54:57]
	v_mfma_f32_16x16x32_bf16 v[50:53], v[164:167], v[172:175], v[50:53]
	v_mfma_f32_16x16x32_bf16 v[38:41], v[146:149], v[184:187], v[38:41]
	v_mfma_f32_16x16x32_bf16 v[34:37], v[164:167], v[184:187], v[34:37]
	v_mfma_f32_16x16x32_bf16 v[22:25], v[146:149], v[192:195], v[22:25]
	v_mfma_f32_16x16x32_bf16 v[18:21], v[164:167], v[192:195], v[18:21]
	v_mfma_f32_16x16x32_bf16 v[6:9], v[146:149], v[200:203], v[6:9]
	v_mfma_f32_16x16x32_bf16 v[2:5], v[164:167], v[200:203], v[2:5]
	v_mfma_f32_16x16x32_bf16 v[54:57], v[150:153], v[176:179], v[54:57]
	v_mfma_f32_16x16x32_bf16 v[50:53], v[168:171], v[176:179], v[50:53]
	v_mfma_f32_16x16x32_bf16 v[38:41], v[150:153], v[188:191], v[38:41]
	v_mfma_f32_16x16x32_bf16 v[34:37], v[168:171], v[188:191], v[34:37]
	v_mfma_f32_16x16x32_bf16 v[22:25], v[150:153], v[196:199], v[22:25]
	v_mfma_f32_16x16x32_bf16 v[18:21], v[168:171], v[196:199], v[18:21]
	v_mfma_f32_16x16x32_bf16 v[6:9], v[150:153], v[204:207], v[6:9]
	v_mfma_f32_16x16x32_bf16 v[2:5], v[168:171], v[204:207], v[2:5]
	s_setprio 0
	s_barrier
; #define PG8_STAGE(bufoff, gbase, voff) do { _Pragma("unroll") for (int _i = 0; _i < 2; ++_i) \
;         __builtin_amdgcn_global_load_lds((const unsigned*)((const char*)(gbase) + (voff)[_i]), (LAS unsigned*)(lds + (bufoff) + ldsw + _i * 8192), 16, 0, 0); } while (0)
; #define PG8_LDA(dst, b, h) do { _Pragma("unroll") for (int m = 0; m < 4; ++m) _Pragma("unroll") for (int k = 0; k < 2; ++k) dst[m][k] = *(const LAS bf16x8*)(lds + PG8_SA(b, h) + aoff + m * 2048 + k * 1024); } while (0)
; #define PG8_LDB(dst, b, h) do { _Pragma("unroll") for (int n = 0; n < 2; ++n) _Pragma("unroll") for (int k = 0; k < 2; ++k) dst[n][k] = *(const LAS bf16x8*)(lds + PG8_SB(b, h) + boff + n * 2048 + k * 1024); } while (0)
; #define PG8_MMA(ai, bj, At, Bt) do { __builtin_amdgcn_s_setprio(1); _Pragma("unroll") for (int m = 0; m < 4; ++m) _Pragma("unroll") for (int n = 0; n < 2; ++n) _Pragma("unroll") for (int k = 0; k < 2; ++k) \
;         acc[ai][bj][m][n] = __builtin_amdgcn_mfma_f32_16x16x32_bf16(Bt[n][k], At[m][k], acc[ai][bj][m][n], 0, 0, 0); __builtin_amdgcn_s_setprio(0); } while (0)
; #define PG8_WAIT_V(n) asm volatile("s_waitcnt vmcnt(" #n ")" ::: "memory")
; #define PG8_WAIT_L(n) asm volatile("s_waitcnt lgkmcnt(" #n ")" ::: "memory")
; #define PG8_BAR __builtin_amdgcn_s_barrier()
; #define PG8_SCHED __builtin_amdgcn_sched_barrier(0)
; template <class Epi, class Sched>
; __device__ __forceinline__ void gemm_phase(LAS unsigned char* lds, const Gemm g, const Sched& S, const Epi& E, int wid_) {
;     ...
;             PG8_LDB(B0, 1, 0); PG8_LDB(B1, 1, 1); PG8_SCHED; PG8_LDA(At, 1, 0); PG8_STAGE(PG8_SA(0, 1), a2 + hstepA, voffA);
;             PG8_WAIT_V(8); PG8_WAIT_L(0); PG8_BAR; PG8_MMA(0, 0, At, B0); PG8_MMA(0, 1, At, B1); PG8_BAR; PG8_SCHED;
;             PG8_LDA(At, 1, 1); PG8_STAGE(PG8_SB(1, 0), b3, voffB); PG8_STAGE(PG8_SB(1, 1), b3 + hstepB, voffB); PG8_STAGE(PG8_SA(1, 0), a3, voffA);
;             PG8_WAIT_V(8); PG8_WAIT_L(0); PG8_BAR; PG8_MMA(1, 0, At, B0); PG8_MMA(1, 1, At, B1); PG8_BAR; PG8_SCHED;
;         }
	s_add_i32 s12, 0, 0x18000
	s_add_i32 s14, 0, 0x1c000
	v_add_u32_e32 v142, s12, v182
	v_add_u32_e32 v168, s14, v182
	ds_read_b128 v[130:133], v142
	ds_read_b128 v[134:137], v142 offset:1024
	ds_read_b128 v[138:141], v142 offset:2048
	ds_read_b128 v[142:145], v142 offset:3072
	ds_read_b128 v[146:149], v168
	ds_read_b128 v[150:153], v168 offset:1024
	ds_read_b128 v[164:167], v168 offset:2048
	ds_read_b128 v[168:171], v168 offset:3072
	s_add_u32 s34, s42, 0x40000
	s_addc_u32 s35, s43, 0
	s_mov_b32 m0, s50
	ds_read_b128 v[172:175], v183 offset:32768
	ds_read_b128 v[176:179], v183 offset:33792
	ds_read_b128 v[184:187], v183 offset:34816
	ds_read_b128 v[188:191], v183 offset:35840
	ds_read_b128 v[192:195], v183 offset:36864
	ds_read_b128 v[196:199], v183 offset:37888
	ds_read_b128 v[200:203], v183 offset:38912
	ds_read_b128 v[204:207], v183 offset:39936
	global_load_lds_dwordx4 v154, s[34:35]
	s_mov_b32 m0, s51
	s_nop 0
	global_load_lds_dwordx4 v156, s[34:35]
	s_waitcnt vmcnt(8)
	s_waitcnt lgkmcnt(0)
	s_barrier
	s_setprio 1
	s_waitcnt lgkmcnt(0)
	v_mfma_f32_16x16x32_bf16 v[126:129], v[130:133], v[172:175], v[126:129]
	v_mfma_f32_16x16x32_bf16 v[122:125], v[138:141], v[172:175], v[122:125]
	v_mfma_f32_16x16x32_bf16 v[110:113], v[130:133], v[184:187], v[110:113]
	v_mfma_f32_16x16x32_bf16 v[106:109], v[138:141], v[184:187], v[106:109]
	v_mfma_f32_16x16x32_bf16 v[94:97], v[130:133], v[192:195], v[94:97]
	v_mfma_f32_16x16x32_bf16 v[90:93], v[138:141], v[192:195], v[90:93]
	v_mfma_f32_16x16x32_bf16 v[78:81], v[130:133], v[200:203], v[78:81]
	v_mfma_f32_16x16x32_bf16 v[74:77], v[138:141], v[200:203], v[74:77]
	v_mfma_f32_16x16x32_bf16 v[126:129], v[134:137], v[176:179], v[126:129]
	v_mfma_f32_16x16x32_bf16 v[122:125], v[142:145], v[176:179], v[122:125]
	v_mfma_f32_16x16x32_bf16 v[110:113], v[134:137], v[188:191], v[110:113]
	v_mfma_f32_16x16x32_bf16 v[106:109], v[142:145], v[188:191], v[106:109]
	v_mfma_f32_16x16x32_bf16 v[94:97], v[134:137], v[196:199], v[94:97]
	v_mfma_f32_16x16x32_bf16 v[90:93], v[142:145], v[196:199], v[90:93]
	v_mfma_f32_16x16x32_bf16 v[78:81], v[134:137], v[204:207], v[78:81]
	v_mfma_f32_16x16x32_bf16 v[74:77], v[142:145], v[204:207], v[74:77]
	s_setprio 0
	s_setprio 1
	v_mfma_f32_16x16x32_bf16 v[118:121], v[146:149], v[172:175], v[118:121]
	v_mfma_f32_16x16x32_bf16 v[114:117], v[164:167], v[172:175], v[114:117]
	v_mfma_f32_16x16x32_bf16 v[102:105], v[146:149], v[184:187], v[102:105]
	v_mfma_f32_16x16x32_bf16 v[98:101], v[164:167], v[184:187], v[98:101]
	v_mfma_f32_16x16x32_bf16 v[86:89], v[146:149], v[192:195], v[86:89]
	v_mfma_f32_16x16x32_bf16 v[82:85], v[164:167], v[192:195], v[82:85]
	v_mfma_f32_16x16x32_bf16 v[70:73], v[146:149], v[200:203], v[70:73]
	v_mfma_f32_16x16x32_bf16 v[66:69], v[164:167], v[200:203], v[66:69]
	v_mfma_f32_16x16x32_bf16 v[118:121], v[150:153], v[176:179], v[118:121]
	v_mfma_f32_16x16x32_bf16 v[114:117], v[168:171], v[176:179], v[114:117]
	v_mfma_f32_16x16x32_bf16 v[102:105], v[150:153], v[188:191], v[102:105]
	v_mfma_f32_16x16x32_bf16 v[98:101], v[168:171], v[188:191], v[98:101]
	v_mfma_f32_16x16x32_bf16 v[86:89], v[150:153], v[196:199], v[86:89]
	v_mfma_f32_16x16x32_bf16 v[82:85], v[168:171], v[196:199], v[82:85]
	v_mfma_f32_16x16x32_bf16 v[70:73], v[150:153], v[204:207], v[70:73]
	v_mfma_f32_16x16x32_bf16 v[66:69], v[168:171], v[204:207], v[66:69]
	s_setprio 0
	s_barrier
	s_add_i32 s12, s12, s46
	s_add_u32 s100, s40, s70
	s_addc_u32 s101, s41, s71
	s_mov_b32 m0, s12
	ds_read_b128 v[172:175], v183 offset:49152
	ds_read_b128 v[176:179], v183 offset:50176
	ds_read_b128 v[184:187], v183 offset:51200
	ds_read_b128 v[188:191], v183 offset:52224
	ds_read_b128 v[192:195], v183 offset:53248
	ds_read_b128 v[196:199], v183 offset:54272
	ds_read_b128 v[200:203], v183 offset:55296
	ds_read_b128 v[204:207], v183 offset:56320
	global_load_lds_dwordx4 v0, s[100:101]
	s_add_i32 m0, s12, 0x2000
	s_add_u32 s34, s40, 0x40080
	s_addc_u32 s35, s41, 0
	s_add_i32 s12, s14, s46
	global_load_lds_dwordx4 v158, s[100:101]
	s_mov_b32 m0, s12
	s_nop 0
	global_load_lds_dwordx4 v0, s[34:35]
	s_add_i32 m0, s12, 0x2000
	s_nop 0
	global_load_lds_dwordx4 v158, s[34:35]
	s_add_u32 s100, s42, s70
	s_addc_u32 s101, s43, s71
	s_mov_b32 m0, s69
	s_nop 0
	global_load_lds_dwordx4 v154, s[100:101]
	s_mov_b32 m0, s80
	s_nop 0
	global_load_lds_dwordx4 v156, s[100:101]
	s_waitcnt vmcnt(8)
	s_waitcnt lgkmcnt(0)
	s_barrier
	s_setprio 1
	s_waitcnt lgkmcnt(0)
	v_mfma_f32_16x16x32_bf16 v[62:65], v[130:133], v[172:175], v[62:65]
	v_mfma_f32_16x16x32_bf16 v[58:61], v[138:141], v[172:175], v[58:61]
	v_mfma_f32_16x16x32_bf16 v[46:49], v[130:133], v[184:187], v[46:49]
	v_mfma_f32_16x16x32_bf16 v[42:45], v[138:141], v[184:187], v[42:45]
	v_mfma_f32_16x16x32_bf16 v[30:33], v[130:133], v[192:195], v[30:33]
	v_mfma_f32_16x16x32_bf16 v[26:29], v[138:141], v[192:195], v[26:29]
	v_mfma_f32_16x16x32_bf16 v[14:17], v[130:133], v[200:203], v[14:17]
	v_mfma_f32_16x16x32_bf16 v[10:13], v[138:141], v[200:203], v[10:13]
	v_mfma_f32_16x16x32_bf16 v[62:65], v[134:137], v[176:179], v[62:65]
	v_mfma_f32_16x16x32_bf16 v[58:61], v[142:145], v[176:179], v[58:61]
	v_mfma_f32_16x16x32_bf16 v[46:49], v[134:137], v[188:191], v[46:49]
	v_mfma_f32_16x16x32_bf16 v[42:45], v[142:145], v[188:191], v[42:45]
	v_mfma_f32_16x16x32_bf16 v[30:33], v[134:137], v[196:199], v[30:33]
	v_mfma_f32_16x16x32_bf16 v[26:29], v[142:145], v[196:199], v[26:29]
	v_mfma_f32_16x16x32_bf16 v[14:17], v[134:137], v[204:207], v[14:17]
	v_mfma_f32_16x16x32_bf16 v[10:13], v[142:145], v[204:207], v[10:13]
	s_setprio 0
	s_setprio 1
	v_mfma_f32_16x16x32_bf16 v[54:57], v[146:149], v[172:175], v[54:57]
	v_mfma_f32_16x16x32_bf16 v[50:53], v[164:167], v[172:175], v[50:53]
	v_mfma_f32_16x16x32_bf16 v[38:41], v[146:149], v[184:187], v[38:41]
	v_mfma_f32_16x16x32_bf16 v[34:37], v[164:167], v[184:187], v[34:37]
	v_mfma_f32_16x16x32_bf16 v[22:25], v[146:149], v[192:195], v[22:25]
	v_mfma_f32_16x16x32_bf16 v[18:21], v[164:167], v[192:195], v[18:21]
	v_mfma_f32_16x16x32_bf16 v[6:9], v[146:149], v[200:203], v[6:9]
	v_mfma_f32_16x16x32_bf16 v[2:5], v[164:167], v[200:203], v[2:5]
	v_mfma_f32_16x16x32_bf16 v[54:57], v[150:153], v[176:179], v[54:57]
	v_mfma_f32_16x16x32_bf16 v[50:53], v[168:171], v[176:179], v[50:53]
	v_mfma_f32_16x16x32_bf16 v[38:41], v[150:153], v[188:191], v[38:41]
	v_mfma_f32_16x16x32_bf16 v[34:37], v[168:171], v[188:191], v[34:37]
	v_mfma_f32_16x16x32_bf16 v[22:25], v[150:153], v[196:199], v[22:25]
	v_mfma_f32_16x16x32_bf16 v[18:21], v[168:171], v[196:199], v[18:21]
	v_mfma_f32_16x16x32_bf16 v[6:9], v[150:153], v[204:207], v[6:9]
	v_mfma_f32_16x16x32_bf16 v[2:5], v[168:171], v[204:207], v[2:5]
	s_setprio 0
	s_barrier
	s_add_i32 s33, s33, 2
	s_add_u32 s38, s38, 0x100
	s_addc_u32 s39, s39, 0
	s_add_u32 s83, s83, 0x100
	s_addc_u32 s54, s54, 0
	s_cmp_gt_u32 s33, 13
	s_cbranch_scc0 .LBB0_435
	s_and_b64 vcc, exec, s[18:19]
	s_cbranch_vccz .LBB0_438
	s_barrier

; #define PG8_STAGE(bufoff, gbase, voff) do { _Pragma("unroll") for (int _i = 0; _i < 2; ++_i) \
;         __builtin_amdgcn_global_load_lds((const unsigned*)((const char*)(gbase) + (voff)[_i]), (LAS unsigned*)(lds + (bufoff) + ldsw + _i * 8192), 16, 0, 0); } while (0)
; #define PG8_LDA(dst, b, h) do { _Pragma("unroll") for (int m = 0; m < 4; ++m) _Pragma("unroll") for (int k = 0; k < 2; ++k) dst[m][k] = *(const LAS bf16x8*)(lds + PG8_SA(b, h) + aoff + m * 2048 + k * 1024); } while (0)
; #define PG8_LDB(dst, b, h) do { _Pragma("unroll") for (int n = 0; n < 2; ++n) _Pragma("unroll") for (int k = 0; k < 2; ++k) dst[n][k] = *(const LAS bf16x8*)(lds + PG8_SB(b, h) + boff + n * 2048 + k * 1024); } while (0)
; #define PG8_MMA(ai, bj, At, Bt) do { __builtin_amdgcn_s_setprio(1); _Pragma("unroll") for (int m = 0; m < 4; ++m) _Pragma("unroll") for (int n = 0; n < 2; ++n) _Pragma("unroll") for (int k = 0; k < 2; ++k) \
;         acc[ai][bj][m][n] = __builtin_amdgcn_mfma_f32_16x16x32_bf16(Bt[n][k], At[m][k], acc[ai][bj][m][n], 0, 0, 0); __builtin_amdgcn_s_setprio(0); } while (0)
; #define PG8_WAIT_V(n) asm volatile("s_waitcnt vmcnt(" #n ")" ::: "memory")
; #define PG8_WAIT_L(n) asm volatile("s_waitcnt lgkmcnt(" #n ")" ::: "memory")
; #define PG8_BAR __builtin_amdgcn_s_barrier()
; #define PG8_SCHED __builtin_amdgcn_sched_barrier(0)
; template <class Epi, class Sched>
; __device__ __forceinline__ void gemm_phase(LAS unsigned char* lds, const Gemm g, const Sched& S, const Epi& E, int wid_) {
;     ...
;             PG8_LDB(B0, 0, 0); PG8_LDB(B1, 0, 1); PG8_SCHED; PG8_LDA(At, 0, 0); PG8_STAGE(PG8_SA(1, 1), a1 + hstepA, voffA);
;             PG8_WAIT_V(8); PG8_WAIT_L(0); PG8_BAR; PG8_MMA(0, 0, At, B0); PG8_MMA(0, 1, At, B1); PG8_BAR; PG8_SCHED;
;             PG8_LDA(At, 0, 1); PG8_STAGE(PG8_SB(0, 0), b2, voffB); PG8_STAGE(PG8_SB(0, 1), b2 + hstepB, voffB); PG8_STAGE(PG8_SA(0, 0), a2, voffA);
;             PG8_WAIT_V(8); PG8_WAIT_L(0); PG8_BAR; PG8_MMA(1, 0, At, B0); PG8_MMA(1, 1, At, B1); PG8_BAR; PG8_SCHED;
.LBB0_527:
	s_add_u32 s12, s6, 0xfffc0080
	s_addc_u32 s14, s7, -1
	s_add_i32 s34, 0, 0x10000
	s_cmp_eq_u32 s33, 12
	s_cselect_b32 s43, s25, s14
	s_cselect_b32 s42, s27, s12
	v_add_u32_e32 v0, s34, v150
	s_cselect_b32 s41, s85, s54
	s_cselect_b32 s40, s87, s89
	s_add_i32 s12, 0, 0x14000
	ds_read_b128 v[142:145], v0
	ds_read_b128 v[146:149], v0 offset:1024
	ds_read_b128 v[152:155], v0 offset:2048
	ds_read_b128 v[156:159], v0 offset:3072
	v_add_u32_e32 v0, s12, v150
	ds_read_b128 v[160:163], v0
	ds_read_b128 v[164:167], v0 offset:1024
	ds_read_b128 v[168:171], v0 offset:2048
	ds_read_b128 v[172:175], v0 offset:3072
	s_add_i32 m0, s47, 0xc000
	ds_read_b128 v[176:179], v151
	ds_read_b128 v[180:183], v151 offset:1024
	ds_read_b128 v[184:187], v151 offset:2048
	ds_read_b128 v[188:191], v151 offset:3072
	ds_read_b128 v[192:195], v151 offset:4096
	ds_read_b128 v[196:199], v151 offset:5120
	ds_read_b128 v[200:203], v151 offset:6144
	ds_read_b128 v[204:207], v151 offset:7168
	global_load_lds_dwordx4 v138, s[6:7]
	s_add_i32 m0, s47, 0xe000
	s_nop 0
	global_load_lds_dwordx4 v140, s[6:7]
	s_waitcnt vmcnt(8)
	s_waitcnt lgkmcnt(0)
	s_barrier
	s_setprio 1
	s_waitcnt lgkmcnt(0)
	v_mfma_f32_16x16x32_bf16 v[126:129], v[142:145], v[176:179], v[126:129]
	v_mfma_f32_16x16x32_bf16 v[122:125], v[152:155], v[176:179], v[122:125]
	v_mfma_f32_16x16x32_bf16 v[110:113], v[142:145], v[184:187], v[110:113]
	v_mfma_f32_16x16x32_bf16 v[106:109], v[152:155], v[184:187], v[106:109]
	v_mfma_f32_16x16x32_bf16 v[94:97], v[142:145], v[192:195], v[94:97]
	v_mfma_f32_16x16x32_bf16 v[90:93], v[152:155], v[192:195], v[90:93]
	v_mfma_f32_16x16x32_bf16 v[78:81], v[142:145], v[200:203], v[78:81]
	v_mfma_f32_16x16x32_bf16 v[74:77], v[152:155], v[200:203], v[74:77]
	v_mfma_f32_16x16x32_bf16 v[126:129], v[146:149], v[180:183], v[126:129]
	v_mfma_f32_16x16x32_bf16 v[122:125], v[156:159], v[180:183], v[122:125]
	v_mfma_f32_16x16x32_bf16 v[110:113], v[146:149], v[188:191], v[110:113]
	v_mfma_f32_16x16x32_bf16 v[106:109], v[156:159], v[188:191], v[106:109]
	v_mfma_f32_16x16x32_bf16 v[94:97], v[146:149], v[196:199], v[94:97]
	v_mfma_f32_16x16x32_bf16 v[90:93], v[156:159], v[196:199], v[90:93]
	v_mfma_f32_16x16x32_bf16 v[78:81], v[146:149], v[204:207], v[78:81]
	v_mfma_f32_16x16x32_bf16 v[74:77], v[156:159], v[204:207], v[74:77]
	s_setprio 0
	s_setprio 1
	v_mfma_f32_16x16x32_bf16 v[118:121], v[160:163], v[176:179], v[118:121]
	v_mfma_f32_16x16x32_bf16 v[114:117], v[168:171], v[176:179], v[114:117]
	v_mfma_f32_16x16x32_bf16 v[102:105], v[160:163], v[184:187], v[102:105]
	v_mfma_f32_16x16x32_bf16 v[98:101], v[168:171], v[184:187], v[98:101]
	v_mfma_f32_16x16x32_bf16 v[86:89], v[160:163], v[192:195], v[86:89]
	v_mfma_f32_16x16x32_bf16 v[82:85], v[168:171], v[192:195], v[82:85]
	v_mfma_f32_16x16x32_bf16 v[70:73], v[160:163], v[200:203], v[70:73]
	v_mfma_f32_16x16x32_bf16 v[66:69], v[168:171], v[200:203], v[66:69]
	v_mfma_f32_16x16x32_bf16 v[118:121], v[164:167], v[180:183], v[118:121]
	v_mfma_f32_16x16x32_bf16 v[114:117], v[172:175], v[180:183], v[114:117]
	v_mfma_f32_16x16x32_bf16 v[102:105], v[164:167], v[188:191], v[102:105]
	v_mfma_f32_16x16x32_bf16 v[98:101], v[172:175], v[188:191], v[98:101]
	v_mfma_f32_16x16x32_bf16 v[86:89], v[164:167], v[196:199], v[86:89]
	v_mfma_f32_16x16x32_bf16 v[82:85], v[172:175], v[196:199], v[82:85]
	v_mfma_f32_16x16x32_bf16 v[70:73], v[164:167], v[204:207], v[70:73]
	v_mfma_f32_16x16x32_bf16 v[66:69], v[172:175], v[204:207], v[66:69]
	s_setprio 0
	s_barrier
	s_add_i32 s14, s34, s46
	s_mov_b32 m0, s14
	ds_read_b128 v[176:179], v151 offset:16384
	ds_read_b128 v[180:183], v151 offset:17408
	ds_read_b128 v[184:187], v151 offset:18432
	ds_read_b128 v[188:191], v151 offset:19456
	ds_read_b128 v[192:195], v151 offset:20480
	ds_read_b128 v[196:199], v151 offset:21504
	ds_read_b128 v[200:203], v151 offset:22528
	ds_read_b128 v[204:207], v151 offset:23552
	global_load_lds_dwordx4 v132, s[40:41]
	s_add_i32 m0, s14, 0x2000
	s_add_u32 s34, s40, 0x40000
	s_addc_u32 s35, s41, 0
	s_add_i32 s12, s12, s46
	global_load_lds_dwordx4 v136, s[40:41]
	s_mov_b32 m0, s12
	s_nop 0
	global_load_lds_dwordx4 v132, s[34:35]
	s_add_i32 m0, s12, 0x2000
	s_nop 0
	global_load_lds_dwordx4 v136, s[34:35]
	s_mov_b32 m0, s47
	s_nop 0
	global_load_lds_dwordx4 v130, s[42:43]
	s_mov_b32 m0, s48
	s_nop 0
	global_load_lds_dwordx4 v134, s[42:43]
	s_waitcnt vmcnt(8)
	s_waitcnt lgkmcnt(0)
	s_barrier
	s_setprio 1
	s_waitcnt lgkmcnt(0)
	v_mfma_f32_16x16x32_bf16 v[62:65], v[142:145], v[176:179], v[62:65]
	v_mfma_f32_16x16x32_bf16 v[58:61], v[152:155], v[176:179], v[58:61]
	v_mfma_f32_16x16x32_bf16 v[46:49], v[142:145], v[184:187], v[46:49]
	v_mfma_f32_16x16x32_bf16 v[42:45], v[152:155], v[184:187], v[42:45]
	v_mfma_f32_16x16x32_bf16 v[30:33], v[142:145], v[192:195], v[30:33]
	v_mfma_f32_16x16x32_bf16 v[26:29], v[152:155], v[192:195], v[26:29]
	v_mfma_f32_16x16x32_bf16 v[14:17], v[142:145], v[200:203], v[14:17]
	v_mfma_f32_16x16x32_bf16 v[10:13], v[152:155], v[200:203], v[10:13]
	v_mfma_f32_16x16x32_bf16 v[62:65], v[146:149], v[180:183], v[62:65]
	v_mfma_f32_16x16x32_bf16 v[58:61], v[156:159], v[180:183], v[58:61]
	v_mfma_f32_16x16x32_bf16 v[46:49], v[146:149], v[188:191], v[46:49]
	v_mfma_f32_16x16x32_bf16 v[42:45], v[156:159], v[188:191], v[42:45]
	v_mfma_f32_16x16x32_bf16 v[30:33], v[146:149], v[196:199], v[30:33]
	v_mfma_f32_16x16x32_bf16 v[26:29], v[156:159], v[196:199], v[26:29]
	v_mfma_f32_16x16x32_bf16 v[14:17], v[146:149], v[204:207], v[14:17]
	v_mfma_f32_16x16x32_bf16 v[10:13], v[156:159], v[204:207], v[10:13]
	s_setprio 0
	s_setprio 1
	v_mfma_f32_16x16x32_bf16 v[54:57], v[160:163], v[176:179], v[54:57]
	v_mfma_f32_16x16x32_bf16 v[50:53], v[168:171], v[176:179], v[50:53]
	v_mfma_f32_16x16x32_bf16 v[38:41], v[160:163], v[184:187], v[38:41]
	v_mfma_f32_16x16x32_bf16 v[34:37], v[168:171], v[184:187], v[34:37]
	v_mfma_f32_16x16x32_bf16 v[22:25], v[160:163], v[192:195], v[22:25]
	v_mfma_f32_16x16x32_bf16 v[18:21], v[168:171], v[192:195], v[18:21]
	v_mfma_f32_16x16x32_bf16 v[6:9], v[160:163], v[200:203], v[6:9]
	v_mfma_f32_16x16x32_bf16 v[2:5], v[168:171], v[200:203], v[2:5]
	v_mfma_f32_16x16x32_bf16 v[54:57], v[164:167], v[180:183], v[54:57]
	v_mfma_f32_16x16x32_bf16 v[50:53], v[172:175], v[180:183], v[50:53]
	v_mfma_f32_16x16x32_bf16 v[38:41], v[164:167], v[188:191], v[38:41]
	v_mfma_f32_16x16x32_bf16 v[34:37], v[172:175], v[188:191], v[34:37]
	v_mfma_f32_16x16x32_bf16 v[22:25], v[164:167], v[196:199], v[22:25]
	v_mfma_f32_16x16x32_bf16 v[18:21], v[172:175], v[196:199], v[18:21]
	v_mfma_f32_16x16x32_bf16 v[6:9], v[164:167], v[204:207], v[6:9]
	v_mfma_f32_16x16x32_bf16 v[2:5], v[172:175], v[204:207], v[2:5]
	s_setprio 0
	s_barrier
; #define PG8_STAGE(bufoff, gbase, voff) do { _Pragma("unroll") for (int _i = 0; _i < 2; ++_i) \
;         __builtin_amdgcn_global_load_lds((const unsigned*)((const char*)(gbase) + (voff)[_i]), (LAS unsigned*)(lds + (bufoff) + ldsw + _i * 8192), 16, 0, 0); } while (0)
; #define PG8_LDA(dst, b, h) do { _Pragma("unroll") for (int m = 0; m < 4; ++m) _Pragma("unroll") for (int k = 0; k < 2; ++k) dst[m][k] = *(const LAS bf16x8*)(lds + PG8_SA(b, h) + aoff + m * 2048 + k * 1024); } while (0)
; #define PG8_LDB(dst, b, h) do { _Pragma("unroll") for (int n = 0; n < 2; ++n) _Pragma("unroll") for (int k = 0; k < 2; ++k) dst[n][k] = *(const LAS bf16x8*)(lds + PG8_SB(b, h) + boff + n * 2048 + k * 1024); } while (0)
; #define PG8_MMA(ai, bj, At, Bt) do { __builtin_amdgcn_s_setprio(1); _Pragma("unroll") for (int m = 0; m < 4; ++m) _Pragma("unroll") for (int n = 0; n < 2; ++n) _Pragma("unroll") for (int k = 0; k < 2; ++k) \
;         acc[ai][bj][m][n] = __builtin_amdgcn_mfma_f32_16x16x32_bf16(Bt[n][k], At[m][k], acc[ai][bj][m][n], 0, 0, 0); __builtin_amdgcn_s_setprio(0); } while (0)
; #define PG8_WAIT_V(n) asm volatile("s_waitcnt vmcnt(" #n ")" ::: "memory")
; #define PG8_WAIT_L(n) asm volatile("s_waitcnt lgkmcnt(" #n ")" ::: "memory")
; #define PG8_BAR __builtin_amdgcn_s_barrier()
; #define PG8_SCHED __builtin_amdgcn_sched_barrier(0)
; template <class Epi, class Sched>
; __device__ __forceinline__ void gemm_phase(LAS unsigned char* lds, const Gemm g, const Sched& S, const Epi& E, int wid_) {
;     ...
;             PG8_LDB(B0, 1, 0); PG8_LDB(B1, 1, 1); PG8_SCHED; PG8_LDA(At, 1, 0); PG8_STAGE(PG8_SA(0, 1), a2 + hstepA, voffA);
;             PG8_WAIT_V(8); PG8_WAIT_L(0); PG8_BAR; PG8_MMA(0, 0, At, B0); PG8_MMA(0, 1, At, B1); PG8_BAR; PG8_SCHED;
;             PG8_LDA(At, 1, 1); PG8_STAGE(PG8_SB(1, 0), b3, voffB); PG8_STAGE(PG8_SB(1, 1), b3 + hstepB, voffB); PG8_STAGE(PG8_SA(1, 0), a3, voffA);
;             PG8_WAIT_V(8); PG8_WAIT_L(0); PG8_BAR; PG8_MMA(1, 0, At, B0); PG8_MMA(1, 1, At, B1); PG8_BAR; PG8_SCHED;
;         }
	s_add_i32 s12, 0, 0x18000
	v_add_u32_e32 v0, s12, v150
	s_add_i32 s14, 0, 0x1c000
	ds_read_b128 v[142:145], v0
	ds_read_b128 v[146:149], v0 offset:1024
	ds_read_b128 v[152:155], v0 offset:2048
	ds_read_b128 v[156:159], v0 offset:3072
	v_add_u32_e32 v0, s14, v150
	ds_read_b128 v[160:163], v0
	ds_read_b128 v[164:167], v0 offset:1024
	ds_read_b128 v[168:171], v0 offset:2048
	ds_read_b128 v[172:175], v0 offset:3072
	s_add_u32 s34, s42, 0x40000
	s_addc_u32 s35, s43, 0
	s_mov_b32 m0, s49
	ds_read_b128 v[176:179], v151 offset:32768
	ds_read_b128 v[180:183], v151 offset:33792
	ds_read_b128 v[184:187], v151 offset:34816
	ds_read_b128 v[188:191], v151 offset:35840
	ds_read_b128 v[192:195], v151 offset:36864
	ds_read_b128 v[196:199], v151 offset:37888
	ds_read_b128 v[200:203], v151 offset:38912
	ds_read_b128 v[204:207], v151 offset:39936
	global_load_lds_dwordx4 v130, s[34:35]
	s_mov_b32 m0, s50
	s_nop 0
	global_load_lds_dwordx4 v134, s[34:35]
	s_waitcnt vmcnt(8)
	s_waitcnt lgkmcnt(0)
	s_barrier
	s_setprio 1
	s_waitcnt lgkmcnt(0)
	v_mfma_f32_16x16x32_bf16 v[126:129], v[142:145], v[176:179], v[126:129]
	v_mfma_f32_16x16x32_bf16 v[122:125], v[152:155], v[176:179], v[122:125]
	v_mfma_f32_16x16x32_bf16 v[110:113], v[142:145], v[184:187], v[110:113]
	v_mfma_f32_16x16x32_bf16 v[106:109], v[152:155], v[184:187], v[106:109]
	v_mfma_f32_16x16x32_bf16 v[94:97], v[142:145], v[192:195], v[94:97]
	v_mfma_f32_16x16x32_bf16 v[90:93], v[152:155], v[192:195], v[90:93]
	v_mfma_f32_16x16x32_bf16 v[78:81], v[142:145], v[200:203], v[78:81]
	v_mfma_f32_16x16x32_bf16 v[74:77], v[152:155], v[200:203], v[74:77]
	v_mfma_f32_16x16x32_bf16 v[126:129], v[146:149], v[180:183], v[126:129]
	v_mfma_f32_16x16x32_bf16 v[122:125], v[156:159], v[180:183], v[122:125]
	v_mfma_f32_16x16x32_bf16 v[110:113], v[146:149], v[188:191], v[110:113]
	v_mfma_f32_16x16x32_bf16 v[106:109], v[156:159], v[188:191], v[106:109]
	v_mfma_f32_16x16x32_bf16 v[94:97], v[146:149], v[196:199], v[94:97]
	v_mfma_f32_16x16x32_bf16 v[90:93], v[156:159], v[196:199], v[90:93]
	v_mfma_f32_16x16x32_bf16 v[78:81], v[146:149], v[204:207], v[78:81]
	v_mfma_f32_16x16x32_bf16 v[74:77], v[156:159], v[204:207], v[74:77]
	s_setprio 0
	s_setprio 1
	v_mfma_f32_16x16x32_bf16 v[118:121], v[160:163], v[176:179], v[118:121]
	v_mfma_f32_16x16x32_bf16 v[114:117], v[168:171], v[176:179], v[114:117]
	v_mfma_f32_16x16x32_bf16 v[102:105], v[160:163], v[184:187], v[102:105]
	v_mfma_f32_16x16x32_bf16 v[98:101], v[168:171], v[184:187], v[98:101]
	v_mfma_f32_16x16x32_bf16 v[86:89], v[160:163], v[192:195], v[86:89]
	v_mfma_f32_16x16x32_bf16 v[82:85], v[168:171], v[192:195], v[82:85]
	v_mfma_f32_16x16x32_bf16 v[70:73], v[160:163], v[200:203], v[70:73]
	v_mfma_f32_16x16x32_bf16 v[66:69], v[168:171], v[200:203], v[66:69]
	v_mfma_f32_16x16x32_bf16 v[118:121], v[164:167], v[180:183], v[118:121]
	v_mfma_f32_16x16x32_bf16 v[114:117], v[172:175], v[180:183], v[114:117]
	v_mfma_f32_16x16x32_bf16 v[102:105], v[164:167], v[188:191], v[102:105]
	v_mfma_f32_16x16x32_bf16 v[98:101], v[172:175], v[188:191], v[98:101]
	v_mfma_f32_16x16x32_bf16 v[86:89], v[164:167], v[196:199], v[86:89]
	v_mfma_f32_16x16x32_bf16 v[82:85], v[172:175], v[196:199], v[82:85]
	v_mfma_f32_16x16x32_bf16 v[70:73], v[164:167], v[204:207], v[70:73]
	v_mfma_f32_16x16x32_bf16 v[66:69], v[172:175], v[204:207], v[66:69]
	s_setprio 0
	s_barrier
	s_add_i32 s12, s12, s46
	s_add_u32 s100, s40, s70
	s_addc_u32 s101, s41, s71
	s_mov_b32 m0, s12
	ds_read_b128 v[176:179], v151 offset:49152
	ds_read_b128 v[180:183], v151 offset:50176
	ds_read_b128 v[184:187], v151 offset:51200
	ds_read_b128 v[188:191], v151 offset:52224
	ds_read_b128 v[192:195], v151 offset:53248
	ds_read_b128 v[196:199], v151 offset:54272
	ds_read_b128 v[200:203], v151 offset:55296
	ds_read_b128 v[204:207], v151 offset:56320
	global_load_lds_dwordx4 v132, s[100:101]
	s_add_i32 m0, s12, 0x2000
	s_add_u32 s34, s40, 0x40080
	s_addc_u32 s35, s41, 0
	s_add_i32 s12, s14, s46
	global_load_lds_dwordx4 v136, s[100:101]
	s_mov_b32 m0, s12
	s_nop 0
	global_load_lds_dwordx4 v132, s[34:35]
	s_add_i32 m0, s12, 0x2000
	s_nop 0
	global_load_lds_dwordx4 v136, s[34:35]
	s_add_u32 s100, s42, s70
	s_addc_u32 s101, s43, s71
	s_mov_b32 m0, s80
	s_nop 0
	global_load_lds_dwordx4 v130, s[100:101]
	s_mov_b32 m0, s81
	s_nop 0
	global_load_lds_dwordx4 v134, s[100:101]
	s_waitcnt vmcnt(8)
	s_waitcnt lgkmcnt(0)
	s_barrier
	s_setprio 1
	s_waitcnt lgkmcnt(0)
	v_mfma_f32_16x16x32_bf16 v[62:65], v[142:145], v[176:179], v[62:65]
	v_mfma_f32_16x16x32_bf16 v[58:61], v[152:155], v[176:179], v[58:61]
	v_mfma_f32_16x16x32_bf16 v[46:49], v[142:145], v[184:187], v[46:49]
	v_mfma_f32_16x16x32_bf16 v[42:45], v[152:155], v[184:187], v[42:45]
	v_mfma_f32_16x16x32_bf16 v[30:33], v[142:145], v[192:195], v[30:33]
	v_mfma_f32_16x16x32_bf16 v[26:29], v[152:155], v[192:195], v[26:29]
	v_mfma_f32_16x16x32_bf16 v[14:17], v[142:145], v[200:203], v[14:17]
	v_mfma_f32_16x16x32_bf16 v[10:13], v[152:155], v[200:203], v[10:13]
	v_mfma_f32_16x16x32_bf16 v[62:65], v[146:149], v[180:183], v[62:65]
	v_mfma_f32_16x16x32_bf16 v[58:61], v[156:159], v[180:183], v[58:61]
	v_mfma_f32_16x16x32_bf16 v[46:49], v[146:149], v[188:191], v[46:49]
	v_mfma_f32_16x16x32_bf16 v[42:45], v[156:159], v[188:191], v[42:45]
	v_mfma_f32_16x16x32_bf16 v[30:33], v[146:149], v[196:199], v[30:33]
	v_mfma_f32_16x16x32_bf16 v[26:29], v[156:159], v[196:199], v[26:29]
	v_mfma_f32_16x16x32_bf16 v[14:17], v[146:149], v[204:207], v[14:17]
	v_mfma_f32_16x16x32_bf16 v[10:13], v[156:159], v[204:207], v[10:13]
	s_setprio 0
	s_setprio 1
	v_mfma_f32_16x16x32_bf16 v[54:57], v[160:163], v[176:179], v[54:57]
	v_mfma_f32_16x16x32_bf16 v[50:53], v[168:171], v[176:179], v[50:53]
	v_mfma_f32_16x16x32_bf16 v[38:41], v[160:163], v[184:187], v[38:41]
	v_mfma_f32_16x16x32_bf16 v[34:37], v[168:171], v[184:187], v[34:37]
	v_mfma_f32_16x16x32_bf16 v[22:25], v[160:163], v[192:195], v[22:25]
	v_mfma_f32_16x16x32_bf16 v[18:21], v[168:171], v[192:195], v[18:21]
	v_mfma_f32_16x16x32_bf16 v[6:9], v[160:163], v[200:203], v[6:9]
	v_mfma_f32_16x16x32_bf16 v[2:5], v[168:171], v[200:203], v[2:5]
	v_mfma_f32_16x16x32_bf16 v[54:57], v[164:167], v[180:183], v[54:57]
	v_mfma_f32_16x16x32_bf16 v[50:53], v[172:175], v[180:183], v[50:53]
	v_mfma_f32_16x16x32_bf16 v[38:41], v[164:167], v[188:191], v[38:41]
	v_mfma_f32_16x16x32_bf16 v[34:37], v[172:175], v[188:191], v[34:37]
	v_mfma_f32_16x16x32_bf16 v[22:25], v[164:167], v[196:199], v[22:25]
	v_mfma_f32_16x16x32_bf16 v[18:21], v[172:175], v[196:199], v[18:21]
	v_mfma_f32_16x16x32_bf16 v[6:9], v[164:167], v[204:207], v[6:9]
	v_mfma_f32_16x16x32_bf16 v[2:5], v[172:175], v[204:207], v[2:5]
	s_setprio 0
	s_barrier
	s_add_i32 s33, s33, 2
	s_add_u32 s6, s6, 0x100
	s_addc_u32 s7, s7, 0
	s_add_u32 s89, s89, 0x100
	s_addc_u32 s54, s54, 0
	s_cmp_gt_u32 s33, 13
	s_cbranch_scc0 .LBB0_527
	s_and_b64 vcc, exec, s[20:21]
	s_cbranch_vccz .LBB0_530
	s_barrier

; #define PG8_STAGE(bufoff, gbase, voff) do { _Pragma("unroll") for (int _i = 0; _i < 2; ++_i) \
;         __builtin_amdgcn_global_load_lds((const unsigned*)((const char*)(gbase) + (voff)[_i]), (LAS unsigned*)(lds + (bufoff) + ldsw + _i * 8192), 16, 0, 0); } while (0)
; #define PG8_LDA(dst, b, h) do { _Pragma("unroll") for (int m = 0; m < 4; ++m) _Pragma("unroll") for (int k = 0; k < 2; ++k) dst[m][k] = *(const LAS bf16x8*)(lds + PG8_SA(b, h) + aoff + m * 2048 + k * 1024); } while (0)
; #define PG8_LDB(dst, b, h) do { _Pragma("unroll") for (int n = 0; n < 2; ++n) _Pragma("unroll") for (int k = 0; k < 2; ++k) dst[n][k] = *(const LAS bf16x8*)(lds + PG8_SB(b, h) + boff + n * 2048 + k * 1024); } while (0)
; #define PG8_MMA(ai, bj, At, Bt) do { __builtin_amdgcn_s_setprio(1); _Pragma("unroll") for (int m = 0; m < 4; ++m) _Pragma("unroll") for (int n = 0; n < 2; ++n) _Pragma("unroll") for (int k = 0; k < 2; ++k) \
;         acc[ai][bj][m][n] = __builtin_amdgcn_mfma_f32_16x16x32_bf16(Bt[n][k], At[m][k], acc[ai][bj][m][n], 0, 0, 0); __builtin_amdgcn_s_setprio(0); } while (0)
; #define PG8_WAIT_V(n) asm volatile("s_waitcnt vmcnt(" #n ")" ::: "memory")
; #define PG8_WAIT_L(n) asm volatile("s_waitcnt lgkmcnt(" #n ")" ::: "memory")
; #define PG8_BAR __builtin_amdgcn_s_barrier()
; #define PG8_SCHED __builtin_amdgcn_sched_barrier(0)
; template <class Epi, class Sched>
; __device__ __forceinline__ void gemm_phase(LAS unsigned char* lds, const Gemm g, const Sched& S, const Epi& E, int wid_) {
;     ...
;             PG8_LDB(B0, 0, 0); PG8_LDB(B1, 0, 1); PG8_SCHED; PG8_LDA(At, 0, 0); PG8_STAGE(PG8_SA(1, 1), a1 + hstepA, voffA);
;             PG8_WAIT_V(8); PG8_WAIT_L(0); PG8_BAR; PG8_MMA(0, 0, At, B0); PG8_MMA(0, 1, At, B1); PG8_BAR; PG8_SCHED;
;             PG8_LDA(At, 0, 1); PG8_STAGE(PG8_SB(0, 0), b2, voffB); PG8_STAGE(PG8_SB(0, 1), b2 + hstepB, voffB); PG8_STAGE(PG8_SA(0, 0), a2, voffA);
;             PG8_WAIT_V(8); PG8_WAIT_L(0); PG8_BAR; PG8_MMA(1, 0, At, B0); PG8_MMA(1, 1, At, B1); PG8_BAR; PG8_SCHED;
.LBB0_649:
	s_add_u32 s12, s38, 0xfffc0080
	s_addc_u32 s14, s39, -1
	s_add_i32 s34, 0, 0x10000
	s_cmp_eq_u32 s33, 12
	s_cselect_b32 s43, s19, s14
	s_cselect_b32 s42, s21, s12
	s_cselect_b32 s41, s82, s54
	s_cselect_b32 s40, s83, s84
	s_add_i32 s12, 0, 0x14000
	v_add_u32_e32 v142, s34, v160
	v_add_u32_e32 v170, s12, v160
	ds_read_b128 v[130:133], v142
	ds_read_b128 v[134:137], v142 offset:1024
	ds_read_b128 v[138:141], v142 offset:2048
	ds_read_b128 v[142:145], v142 offset:3072
	ds_read_b128 v[156:159], v170
	ds_read_b128 v[162:165], v170 offset:1024
	ds_read_b128 v[166:169], v170 offset:2048
	ds_read_b128 v[170:173], v170 offset:3072
	s_add_i32 m0, s47, 0xc000
	ds_read_b128 v[174:177], v161
	ds_read_b128 v[178:181], v161 offset:1024
	ds_read_b128 v[182:185], v161 offset:2048
	ds_read_b128 v[186:189], v161 offset:3072
	ds_read_b128 v[190:193], v161 offset:4096
	ds_read_b128 v[194:197], v161 offset:5120
	ds_read_b128 v[198:201], v161 offset:6144
	ds_read_b128 v[202:205], v161 offset:7168
	global_load_lds_dwordx4 v152, s[38:39]
	s_add_i32 m0, s47, 0xe000
	s_nop 0
	global_load_lds_dwordx4 v154, s[38:39]
	s_waitcnt vmcnt(8)
	s_waitcnt lgkmcnt(0)
	s_barrier
	s_setprio 1
	s_waitcnt lgkmcnt(0)
	v_mfma_f32_16x16x32_bf16 v[126:129], v[130:133], v[174:177], v[126:129]
	v_mfma_f32_16x16x32_bf16 v[122:125], v[138:141], v[174:177], v[122:125]
	v_mfma_f32_16x16x32_bf16 v[118:121], v[130:133], v[182:185], v[118:121]
	v_mfma_f32_16x16x32_bf16 v[110:113], v[138:141], v[182:185], v[110:113]
	v_mfma_f32_16x16x32_bf16 v[102:105], v[130:133], v[190:193], v[102:105]
	v_mfma_f32_16x16x32_bf16 v[94:97], v[138:141], v[190:193], v[94:97]
	v_mfma_f32_16x16x32_bf16 v[86:89], v[130:133], v[198:201], v[86:89]
	v_mfma_f32_16x16x32_bf16 v[78:81], v[138:141], v[198:201], v[78:81]
	v_mfma_f32_16x16x32_bf16 v[126:129], v[134:137], v[178:181], v[126:129]
	v_mfma_f32_16x16x32_bf16 v[122:125], v[142:145], v[178:181], v[122:125]
	v_mfma_f32_16x16x32_bf16 v[118:121], v[134:137], v[186:189], v[118:121]
	v_mfma_f32_16x16x32_bf16 v[110:113], v[142:145], v[186:189], v[110:113]
	v_mfma_f32_16x16x32_bf16 v[102:105], v[134:137], v[194:197], v[102:105]
	v_mfma_f32_16x16x32_bf16 v[94:97], v[142:145], v[194:197], v[94:97]
	v_mfma_f32_16x16x32_bf16 v[86:89], v[134:137], v[202:205], v[86:89]
	v_mfma_f32_16x16x32_bf16 v[78:81], v[142:145], v[202:205], v[78:81]
	s_setprio 0
	s_setprio 1
	v_mfma_f32_16x16x32_bf16 v[114:117], v[156:159], v[174:177], v[114:117]
	v_mfma_f32_16x16x32_bf16 v[106:109], v[166:169], v[174:177], v[106:109]
	v_mfma_f32_16x16x32_bf16 v[98:101], v[156:159], v[182:185], v[98:101]
	v_mfma_f32_16x16x32_bf16 v[90:93], v[166:169], v[182:185], v[90:93]
	v_mfma_f32_16x16x32_bf16 v[82:85], v[156:159], v[190:193], v[82:85]
	v_mfma_f32_16x16x32_bf16 v[74:77], v[166:169], v[190:193], v[74:77]
	v_mfma_f32_16x16x32_bf16 v[70:73], v[156:159], v[198:201], v[70:73]
	v_mfma_f32_16x16x32_bf16 v[66:69], v[166:169], v[198:201], v[66:69]
	v_mfma_f32_16x16x32_bf16 v[114:117], v[162:165], v[178:181], v[114:117]
	v_mfma_f32_16x16x32_bf16 v[106:109], v[170:173], v[178:181], v[106:109]
	v_mfma_f32_16x16x32_bf16 v[98:101], v[162:165], v[186:189], v[98:101]
	v_mfma_f32_16x16x32_bf16 v[90:93], v[170:173], v[186:189], v[90:93]
	v_mfma_f32_16x16x32_bf16 v[82:85], v[162:165], v[194:197], v[82:85]
	v_mfma_f32_16x16x32_bf16 v[74:77], v[170:173], v[194:197], v[74:77]
	v_mfma_f32_16x16x32_bf16 v[70:73], v[162:165], v[202:205], v[70:73]
	v_mfma_f32_16x16x32_bf16 v[66:69], v[170:173], v[202:205], v[66:69]
	s_setprio 0
	s_barrier
	s_add_i32 s14, s34, s37
	s_mov_b32 m0, s14
	ds_read_b128 v[174:177], v161 offset:16384
	ds_read_b128 v[178:181], v161 offset:17408
	ds_read_b128 v[182:185], v161 offset:18432
	ds_read_b128 v[186:189], v161 offset:19456
	ds_read_b128 v[190:193], v161 offset:20480
	ds_read_b128 v[194:197], v161 offset:21504
	ds_read_b128 v[198:201], v161 offset:22528
	ds_read_b128 v[202:205], v161 offset:23552
	global_load_lds_dwordx4 v0, s[40:41]
	s_add_i32 m0, s14, 0x2000
	s_add_u32 s34, s40, 0x40000
	s_addc_u32 s35, s41, 0
	s_add_i32 s12, s12, s37
	global_load_lds_dwordx4 v150, s[40:41]
	s_mov_b32 m0, s12
	s_nop 0
	global_load_lds_dwordx4 v0, s[34:35]
	s_add_i32 m0, s12, 0x2000
	s_nop 0
	global_load_lds_dwordx4 v150, s[34:35]
	s_mov_b32 m0, s47
	s_nop 0
	global_load_lds_dwordx4 v146, s[42:43]
	s_mov_b32 m0, s48
	s_nop 0
	global_load_lds_dwordx4 v148, s[42:43]
	s_waitcnt vmcnt(8)
	s_waitcnt lgkmcnt(0)
	s_barrier
	s_setprio 1
	s_waitcnt lgkmcnt(0)
	v_mfma_f32_16x16x32_bf16 v[62:65], v[130:133], v[174:177], v[62:65]
	v_mfma_f32_16x16x32_bf16 v[58:61], v[138:141], v[174:177], v[58:61]
	v_mfma_f32_16x16x32_bf16 v[54:57], v[130:133], v[182:185], v[54:57]
	v_mfma_f32_16x16x32_bf16 v[46:49], v[138:141], v[182:185], v[46:49]
	v_mfma_f32_16x16x32_bf16 v[38:41], v[130:133], v[190:193], v[38:41]
	v_mfma_f32_16x16x32_bf16 v[30:33], v[138:141], v[190:193], v[30:33]
	v_mfma_f32_16x16x32_bf16 v[22:25], v[130:133], v[198:201], v[22:25]
	v_mfma_f32_16x16x32_bf16 v[14:17], v[138:141], v[198:201], v[14:17]
	v_mfma_f32_16x16x32_bf16 v[62:65], v[134:137], v[178:181], v[62:65]
	v_mfma_f32_16x16x32_bf16 v[58:61], v[142:145], v[178:181], v[58:61]
	v_mfma_f32_16x16x32_bf16 v[54:57], v[134:137], v[186:189], v[54:57]
	v_mfma_f32_16x16x32_bf16 v[46:49], v[142:145], v[186:189], v[46:49]
	v_mfma_f32_16x16x32_bf16 v[38:41], v[134:137], v[194:197], v[38:41]
	v_mfma_f32_16x16x32_bf16 v[30:33], v[142:145], v[194:197], v[30:33]
	v_mfma_f32_16x16x32_bf16 v[22:25], v[134:137], v[202:205], v[22:25]
	v_mfma_f32_16x16x32_bf16 v[14:17], v[142:145], v[202:205], v[14:17]
	s_setprio 0
	s_setprio 1
	v_mfma_f32_16x16x32_bf16 v[50:53], v[156:159], v[174:177], v[50:53]
	v_mfma_f32_16x16x32_bf16 v[42:45], v[166:169], v[174:177], v[42:45]
	v_mfma_f32_16x16x32_bf16 v[34:37], v[156:159], v[182:185], v[34:37]
	v_mfma_f32_16x16x32_bf16 v[26:29], v[166:169], v[182:185], v[26:29]
	v_mfma_f32_16x16x32_bf16 v[18:21], v[156:159], v[190:193], v[18:21]
	v_mfma_f32_16x16x32_bf16 v[10:13], v[166:169], v[190:193], v[10:13]
	v_mfma_f32_16x16x32_bf16 v[6:9], v[156:159], v[198:201], v[6:9]
	v_mfma_f32_16x16x32_bf16 v[2:5], v[166:169], v[198:201], v[2:5]
	v_mfma_f32_16x16x32_bf16 v[50:53], v[162:165], v[178:181], v[50:53]
	v_mfma_f32_16x16x32_bf16 v[42:45], v[170:173], v[178:181], v[42:45]
	v_mfma_f32_16x16x32_bf16 v[34:37], v[162:165], v[186:189], v[34:37]
	v_mfma_f32_16x16x32_bf16 v[26:29], v[170:173], v[186:189], v[26:29]
	v_mfma_f32_16x16x32_bf16 v[18:21], v[162:165], v[194:197], v[18:21]
	v_mfma_f32_16x16x32_bf16 v[10:13], v[170:173], v[194:197], v[10:13]
	v_mfma_f32_16x16x32_bf16 v[6:9], v[162:165], v[202:205], v[6:9]
	v_mfma_f32_16x16x32_bf16 v[2:5], v[170:173], v[202:205], v[2:5]
	s_setprio 0
	s_barrier
; #define PG8_STAGE(bufoff, gbase, voff) do { _Pragma("unroll") for (int _i = 0; _i < 2; ++_i) \
;         __builtin_amdgcn_global_load_lds((const unsigned*)((const char*)(gbase) + (voff)[_i]), (LAS unsigned*)(lds + (bufoff) + ldsw + _i * 8192), 16, 0, 0); } while (0)
; #define PG8_LDA(dst, b, h) do { _Pragma("unroll") for (int m = 0; m < 4; ++m) _Pragma("unroll") for (int k = 0; k < 2; ++k) dst[m][k] = *(const LAS bf16x8*)(lds + PG8_SA(b, h) + aoff + m * 2048 + k * 1024); } while (0)
; #define PG8_LDB(dst, b, h) do { _Pragma("unroll") for (int n = 0; n < 2; ++n) _Pragma("unroll") for (int k = 0; k < 2; ++k) dst[n][k] = *(const LAS bf16x8*)(lds + PG8_SB(b, h) + boff + n * 2048 + k * 1024); } while (0)
; #define PG8_MMA(ai, bj, At, Bt) do { __builtin_amdgcn_s_setprio(1); _Pragma("unroll") for (int m = 0; m < 4; ++m) _Pragma("unroll") for (int n = 0; n < 2; ++n) _Pragma("unroll") for (int k = 0; k < 2; ++k) \
;         acc[ai][bj][m][n] = __builtin_amdgcn_mfma_f32_16x16x32_bf16(Bt[n][k], At[m][k], acc[ai][bj][m][n], 0, 0, 0); __builtin_amdgcn_s_setprio(0); } while (0)
; #define PG8_WAIT_V(n) asm volatile("s_waitcnt vmcnt(" #n ")" ::: "memory")
; #define PG8_WAIT_L(n) asm volatile("s_waitcnt lgkmcnt(" #n ")" ::: "memory")
; #define PG8_BAR __builtin_amdgcn_s_barrier()
; #define PG8_SCHED __builtin_amdgcn_sched_barrier(0)
; template <class Epi, class Sched>
; __device__ __forceinline__ void gemm_phase(LAS unsigned char* lds, const Gemm g, const Sched& S, const Epi& E, int wid_) {
;     ...
;             PG8_LDB(B0, 1, 0); PG8_LDB(B1, 1, 1); PG8_SCHED; PG8_LDA(At, 1, 0); PG8_STAGE(PG8_SA(0, 1), a2 + hstepA, voffA);
;             PG8_WAIT_V(8); PG8_WAIT_L(0); PG8_BAR; PG8_MMA(0, 0, At, B0); PG8_MMA(0, 1, At, B1); PG8_BAR; PG8_SCHED;
;             PG8_LDA(At, 1, 1); PG8_STAGE(PG8_SB(1, 0), b3, voffB); PG8_STAGE(PG8_SB(1, 1), b3 + hstepB, voffB); PG8_STAGE(PG8_SA(1, 0), a3, voffA);
;             PG8_WAIT_V(8); PG8_WAIT_L(0); PG8_BAR; PG8_MMA(1, 0, At, B0); PG8_MMA(1, 1, At, B1); PG8_BAR; PG8_SCHED;
;         }
	s_add_i32 s12, 0, 0x18000
	s_add_i32 s14, 0, 0x1c000
	v_add_u32_e32 v142, s12, v160
	v_add_u32_e32 v170, s14, v160
	ds_read_b128 v[130:133], v142
	ds_read_b128 v[134:137], v142 offset:1024
	ds_read_b128 v[138:141], v142 offset:2048
	ds_read_b128 v[142:145], v142 offset:3072
	ds_read_b128 v[156:159], v170
	ds_read_b128 v[162:165], v170 offset:1024
	ds_read_b128 v[166:169], v170 offset:2048
	ds_read_b128 v[170:173], v170 offset:3072
	s_add_u32 s34, s42, 0x40000
	s_addc_u32 s35, s43, 0
	s_mov_b32 m0, s49
	ds_read_b128 v[174:177], v161 offset:32768
	ds_read_b128 v[178:181], v161 offset:33792
	ds_read_b128 v[182:185], v161 offset:34816
	ds_read_b128 v[186:189], v161 offset:35840
	ds_read_b128 v[190:193], v161 offset:36864
	ds_read_b128 v[194:197], v161 offset:37888
	ds_read_b128 v[198:201], v161 offset:38912
	ds_read_b128 v[202:205], v161 offset:39936
	global_load_lds_dwordx4 v146, s[34:35]
	s_mov_b32 m0, s50
	s_nop 0
	global_load_lds_dwordx4 v148, s[34:35]
	s_waitcnt vmcnt(8)
	s_waitcnt lgkmcnt(0)
	s_barrier
	s_setprio 1
	s_waitcnt lgkmcnt(0)
	v_mfma_f32_16x16x32_bf16 v[126:129], v[130:133], v[174:177], v[126:129]
	v_mfma_f32_16x16x32_bf16 v[122:125], v[138:141], v[174:177], v[122:125]
	v_mfma_f32_16x16x32_bf16 v[118:121], v[130:133], v[182:185], v[118:121]
	v_mfma_f32_16x16x32_bf16 v[110:113], v[138:141], v[182:185], v[110:113]
	v_mfma_f32_16x16x32_bf16 v[102:105], v[130:133], v[190:193], v[102:105]
	v_mfma_f32_16x16x32_bf16 v[94:97], v[138:141], v[190:193], v[94:97]
	v_mfma_f32_16x16x32_bf16 v[86:89], v[130:133], v[198:201], v[86:89]
	v_mfma_f32_16x16x32_bf16 v[78:81], v[138:141], v[198:201], v[78:81]
	v_mfma_f32_16x16x32_bf16 v[126:129], v[134:137], v[178:181], v[126:129]
	v_mfma_f32_16x16x32_bf16 v[122:125], v[142:145], v[178:181], v[122:125]
	v_mfma_f32_16x16x32_bf16 v[118:121], v[134:137], v[186:189], v[118:121]
	v_mfma_f32_16x16x32_bf16 v[110:113], v[142:145], v[186:189], v[110:113]
	v_mfma_f32_16x16x32_bf16 v[102:105], v[134:137], v[194:197], v[102:105]
	v_mfma_f32_16x16x32_bf16 v[94:97], v[142:145], v[194:197], v[94:97]
	v_mfma_f32_16x16x32_bf16 v[86:89], v[134:137], v[202:205], v[86:89]
	v_mfma_f32_16x16x32_bf16 v[78:81], v[142:145], v[202:205], v[78:81]
	s_setprio 0
	s_setprio 1
	v_mfma_f32_16x16x32_bf16 v[114:117], v[156:159], v[174:177], v[114:117]
	v_mfma_f32_16x16x32_bf16 v[106:109], v[166:169], v[174:177], v[106:109]
	v_mfma_f32_16x16x32_bf16 v[98:101], v[156:159], v[182:185], v[98:101]
	v_mfma_f32_16x16x32_bf16 v[90:93], v[166:169], v[182:185], v[90:93]
	v_mfma_f32_16x16x32_bf16 v[82:85], v[156:159], v[190:193], v[82:85]
	v_mfma_f32_16x16x32_bf16 v[74:77], v[166:169], v[190:193], v[74:77]
	v_mfma_f32_16x16x32_bf16 v[70:73], v[156:159], v[198:201], v[70:73]
	v_mfma_f32_16x16x32_bf16 v[66:69], v[166:169], v[198:201], v[66:69]
	v_mfma_f32_16x16x32_bf16 v[114:117], v[162:165], v[178:181], v[114:117]
	v_mfma_f32_16x16x32_bf16 v[106:109], v[170:173], v[178:181], v[106:109]
	v_mfma_f32_16x16x32_bf16 v[98:101], v[162:165], v[186:189], v[98:101]
	v_mfma_f32_16x16x32_bf16 v[90:93], v[170:173], v[186:189], v[90:93]
	v_mfma_f32_16x16x32_bf16 v[82:85], v[162:165], v[194:197], v[82:85]
	v_mfma_f32_16x16x32_bf16 v[74:77], v[170:173], v[194:197], v[74:77]
	v_mfma_f32_16x16x32_bf16 v[70:73], v[162:165], v[202:205], v[70:73]
	v_mfma_f32_16x16x32_bf16 v[66:69], v[170:173], v[202:205], v[66:69]
	s_setprio 0
	s_barrier
	s_add_i32 s12, s12, s37
	s_add_u32 s100, s40, s70
	s_addc_u32 s101, s41, s71
	s_mov_b32 m0, s12
	ds_read_b128 v[174:177], v161 offset:49152
	ds_read_b128 v[178:181], v161 offset:50176
	ds_read_b128 v[182:185], v161 offset:51200
	ds_read_b128 v[186:189], v161 offset:52224
	ds_read_b128 v[190:193], v161 offset:53248
	ds_read_b128 v[194:197], v161 offset:54272
	ds_read_b128 v[198:201], v161 offset:55296
	ds_read_b128 v[202:205], v161 offset:56320
	global_load_lds_dwordx4 v0, s[100:101]
	s_add_i32 m0, s12, 0x2000
	s_add_u32 s34, s40, 0x40080
	s_addc_u32 s35, s41, 0
	s_add_i32 s12, s14, s37
	global_load_lds_dwordx4 v150, s[100:101]
	s_mov_b32 m0, s12
	s_nop 0
	global_load_lds_dwordx4 v0, s[34:35]
	s_add_i32 m0, s12, 0x2000
	s_nop 0
	global_load_lds_dwordx4 v150, s[34:35]
	s_add_u32 s100, s42, s70
	s_addc_u32 s101, s43, s71
	s_mov_b32 m0, s69
	s_nop 0
	global_load_lds_dwordx4 v146, s[100:101]
	s_mov_b32 m0, s80
	s_nop 0
	global_load_lds_dwordx4 v148, s[100:101]
	s_waitcnt vmcnt(8)
	s_waitcnt lgkmcnt(0)
	s_barrier
	s_setprio 1
	s_waitcnt lgkmcnt(0)
	v_mfma_f32_16x16x32_bf16 v[62:65], v[130:133], v[174:177], v[62:65]
	v_mfma_f32_16x16x32_bf16 v[58:61], v[138:141], v[174:177], v[58:61]
	v_mfma_f32_16x16x32_bf16 v[54:57], v[130:133], v[182:185], v[54:57]
	v_mfma_f32_16x16x32_bf16 v[46:49], v[138:141], v[182:185], v[46:49]
	v_mfma_f32_16x16x32_bf16 v[38:41], v[130:133], v[190:193], v[38:41]
	v_mfma_f32_16x16x32_bf16 v[30:33], v[138:141], v[190:193], v[30:33]
	v_mfma_f32_16x16x32_bf16 v[22:25], v[130:133], v[198:201], v[22:25]
	v_mfma_f32_16x16x32_bf16 v[14:17], v[138:141], v[198:201], v[14:17]
	v_mfma_f32_16x16x32_bf16 v[62:65], v[134:137], v[178:181], v[62:65]
	v_mfma_f32_16x16x32_bf16 v[58:61], v[142:145], v[178:181], v[58:61]
	v_mfma_f32_16x16x32_bf16 v[54:57], v[134:137], v[186:189], v[54:57]
	v_mfma_f32_16x16x32_bf16 v[46:49], v[142:145], v[186:189], v[46:49]
	v_mfma_f32_16x16x32_bf16 v[38:41], v[134:137], v[194:197], v[38:41]
	v_mfma_f32_16x16x32_bf16 v[30:33], v[142:145], v[194:197], v[30:33]
	v_mfma_f32_16x16x32_bf16 v[22:25], v[134:137], v[202:205], v[22:25]
	v_mfma_f32_16x16x32_bf16 v[14:17], v[142:145], v[202:205], v[14:17]
	s_setprio 0
	s_setprio 1
	v_mfma_f32_16x16x32_bf16 v[50:53], v[156:159], v[174:177], v[50:53]
	v_mfma_f32_16x16x32_bf16 v[42:45], v[166:169], v[174:177], v[42:45]
	v_mfma_f32_16x16x32_bf16 v[34:37], v[156:159], v[182:185], v[34:37]
	v_mfma_f32_16x16x32_bf16 v[26:29], v[166:169], v[182:185], v[26:29]
	v_mfma_f32_16x16x32_bf16 v[18:21], v[156:159], v[190:193], v[18:21]
	v_mfma_f32_16x16x32_bf16 v[10:13], v[166:169], v[190:193], v[10:13]
	v_mfma_f32_16x16x32_bf16 v[6:9], v[156:159], v[198:201], v[6:9]
	v_mfma_f32_16x16x32_bf16 v[2:5], v[166:169], v[198:201], v[2:5]
	v_mfma_f32_16x16x32_bf16 v[50:53], v[162:165], v[178:181], v[50:53]
	v_mfma_f32_16x16x32_bf16 v[42:45], v[170:173], v[178:181], v[42:45]
	v_mfma_f32_16x16x32_bf16 v[34:37], v[162:165], v[186:189], v[34:37]
	v_mfma_f32_16x16x32_bf16 v[26:29], v[170:173], v[186:189], v[26:29]
	v_mfma_f32_16x16x32_bf16 v[18:21], v[162:165], v[194:197], v[18:21]
	v_mfma_f32_16x16x32_bf16 v[10:13], v[170:173], v[194:197], v[10:13]
	v_mfma_f32_16x16x32_bf16 v[6:9], v[162:165], v[202:205], v[6:9]
	v_mfma_f32_16x16x32_bf16 v[2:5], v[170:173], v[202:205], v[2:5]
	s_setprio 0
	s_barrier
	s_add_i32 s33, s33, 2
	s_add_u32 s38, s38, 0x100
	s_addc_u32 s39, s39, 0
	s_add_u32 s84, s84, 0x100
	s_addc_u32 s54, s54, 0
	s_cmp_gt_u32 s33, 13
	s_cbranch_scc0 .LBB0_649
	s_and_b64 vcc, exec, s[10:11]
	s_cbranch_vccz .LBB0_652
	s_barrier

; #define PG8_STAGE(bufoff, gbase, voff) do { _Pragma("unroll") for (int _i = 0; _i < 2; ++_i) \
;         __builtin_amdgcn_global_load_lds((const unsigned*)((const char*)(gbase) + (voff)[_i]), (LAS unsigned*)(lds + (bufoff) + ldsw + _i * 8192), 16, 0, 0); } while (0)
; #define PG8_LDA(dst, b, h) do { _Pragma("unroll") for (int m = 0; m < 4; ++m) _Pragma("unroll") for (int k = 0; k < 2; ++k) dst[m][k] = *(const LAS bf16x8*)(lds + PG8_SA(b, h) + aoff + m * 2048 + k * 1024); } while (0)
; #define PG8_LDB(dst, b, h) do { _Pragma("unroll") for (int n = 0; n < 2; ++n) _Pragma("unroll") for (int k = 0; k < 2; ++k) dst[n][k] = *(const LAS bf16x8*)(lds + PG8_SB(b, h) + boff + n * 2048 + k * 1024); } while (0)
; #define PG8_MMA(ai, bj, At, Bt) do { __builtin_amdgcn_s_setprio(1); _Pragma("unroll") for (int m = 0; m < 4; ++m) _Pragma("unroll") for (int n = 0; n < 2; ++n) _Pragma("unroll") for (int k = 0; k < 2; ++k) \
;         acc[ai][bj][m][n] = __builtin_amdgcn_mfma_f32_16x16x32_bf16(Bt[n][k], At[m][k], acc[ai][bj][m][n], 0, 0, 0); __builtin_amdgcn_s_setprio(0); } while (0)
; #define PG8_WAIT_V(n) asm volatile("s_waitcnt vmcnt(" #n ")" ::: "memory")
; #define PG8_WAIT_L(n) asm volatile("s_waitcnt lgkmcnt(" #n ")" ::: "memory")
; #define PG8_BAR __builtin_amdgcn_s_barrier()
; #define PG8_SCHED __builtin_amdgcn_sched_barrier(0)
; template <class Epi, class Sched>
; __device__ __forceinline__ void gemm_phase(LAS unsigned char* lds, const Gemm g, const Sched& S, const Epi& E, int wid_) {
;     ...
;             const bool last = (t == nt - 2);
;             const char* a1 = cA + (size_t)(t + 1) * kstep;
;             const char* a2 = last ? nA : cA + (size_t)(t + 2) * kstep; const char* b2 = last ? nB : cB + (size_t)(t + 2) * kstep;
;             const char* a3 = a2 + kstep; const char* b3 = b2 + kstep;
;             PG8_LDB(B0, 0, 0); PG8_LDB(B1, 0, 1); PG8_SCHED; PG8_LDA(At, 0, 0); PG8_STAGE(PG8_SA(1, 1), a1 + hstepA, voffA);
;             PG8_WAIT_V(8); PG8_WAIT_L(0); PG8_BAR; PG8_MMA(0, 0, At, B0); PG8_MMA(0, 1, At, B1); PG8_BAR; PG8_SCHED;
;             PG8_LDA(At, 0, 1); PG8_STAGE(PG8_SB(0, 0), b2, voffB); PG8_STAGE(PG8_SB(0, 1), b2 + hstepB, voffB); PG8_STAGE(PG8_SA(0, 0), a2, voffA);
;             PG8_WAIT_V(8); PG8_WAIT_L(0); PG8_BAR; PG8_MMA(1, 0, At, B0); PG8_MMA(1, 1, At, B1); PG8_BAR; PG8_SCHED;
.LBB0_856:
	s_add_u32 s34, s44, 0xfffc0080
	s_addc_u32 s35, s45, -1
	s_add_i32 s12, 0, 0x10000
	s_cmp_eq_u32 s33, 12
	s_cselect_b32 s49, s29, s35
	s_cselect_b32 s48, s31, s34
	v_add_u32_e32 v148, s12, v149
	s_cselect_b32 s47, vcc_lo, s54
	s_cselect_b32 s46, vcc_hi, s93
	s_add_i32 s14, 0, 0x14000
	ds_read_b128 v[30:33], v148
	ds_read_b128 v[38:41], v148 offset:1024
	ds_read_b128 v[150:153], v148 offset:2048
	ds_read_b128 v[158:161], v148 offset:3072
	v_add_u32_e32 v148, s14, v149
	ds_read_b128 v[162:165], v148
	ds_read_b128 v[166:169], v148 offset:1024
	ds_read_b128 v[170:173], v148 offset:2048
	ds_read_b128 v[174:177], v148 offset:3072
	s_add_i32 m0, s84, 0xc000
	ds_read_b128 v[178:181], v156
	ds_read_b128 v[182:185], v156 offset:1024
	ds_read_b128 v[186:189], v156 offset:2048
	ds_read_b128 v[190:193], v156 offset:3072
	ds_read_b128 v[194:197], v156 offset:4096
	ds_read_b128 v[198:201], v156 offset:5120
	ds_read_b128 v[202:205], v156 offset:6144
	ds_read_b128 v[212:215], v156 offset:7168
	global_load_lds_dwordx4 v144, s[44:45]
	s_add_i32 m0, s84, 0xe000
	s_nop 0
	global_load_lds_dwordx4 v146, s[44:45]
	s_waitcnt vmcnt(8)
	s_waitcnt lgkmcnt(0)
	s_barrier
	s_setprio 1
	s_waitcnt lgkmcnt(0)
	v_mfma_f32_16x16x32_bf16 v[134:137], v[30:33], v[178:181], v[134:137]
	v_mfma_f32_16x16x32_bf16 v[130:133], v[150:153], v[178:181], v[130:133]
	v_mfma_f32_16x16x32_bf16 v[118:121], v[30:33], v[186:189], v[118:121]
	v_mfma_f32_16x16x32_bf16 v[114:117], v[150:153], v[186:189], v[114:117]
	v_mfma_f32_16x16x32_bf16 v[102:105], v[30:33], v[194:197], v[102:105]
	v_mfma_f32_16x16x32_bf16 v[98:101], v[150:153], v[194:197], v[98:101]
	v_mfma_f32_16x16x32_bf16 v[86:89], v[30:33], v[202:205], v[86:89]
	v_mfma_f32_16x16x32_bf16 v[82:85], v[150:153], v[202:205], v[82:85]
	v_mfma_f32_16x16x32_bf16 v[134:137], v[38:41], v[182:185], v[134:137]
	v_mfma_f32_16x16x32_bf16 v[130:133], v[158:161], v[182:185], v[130:133]
	v_mfma_f32_16x16x32_bf16 v[118:121], v[38:41], v[190:193], v[118:121]
	v_mfma_f32_16x16x32_bf16 v[114:117], v[158:161], v[190:193], v[114:117]
	v_mfma_f32_16x16x32_bf16 v[102:105], v[38:41], v[198:201], v[102:105]
	v_mfma_f32_16x16x32_bf16 v[98:101], v[158:161], v[198:201], v[98:101]
	v_mfma_f32_16x16x32_bf16 v[86:89], v[38:41], v[212:215], v[86:89]
	v_mfma_f32_16x16x32_bf16 v[82:85], v[158:161], v[212:215], v[82:85]
	s_setprio 0
	s_setprio 1
	v_mfma_f32_16x16x32_bf16 v[126:129], v[162:165], v[178:181], v[126:129]
	v_mfma_f32_16x16x32_bf16 v[122:125], v[170:173], v[178:181], v[122:125]
	v_mfma_f32_16x16x32_bf16 v[110:113], v[162:165], v[186:189], v[110:113]
	v_mfma_f32_16x16x32_bf16 v[106:109], v[170:173], v[186:189], v[106:109]
	v_mfma_f32_16x16x32_bf16 v[94:97], v[162:165], v[194:197], v[94:97]
	v_mfma_f32_16x16x32_bf16 v[90:93], v[170:173], v[194:197], v[90:93]
	v_mfma_f32_16x16x32_bf16 v[78:81], v[162:165], v[202:205], v[78:81]
	v_mfma_f32_16x16x32_bf16 v[74:77], v[170:173], v[202:205], v[74:77]
	v_mfma_f32_16x16x32_bf16 v[126:129], v[166:169], v[182:185], v[126:129]
	v_mfma_f32_16x16x32_bf16 v[122:125], v[174:177], v[182:185], v[122:125]
	v_mfma_f32_16x16x32_bf16 v[110:113], v[166:169], v[190:193], v[110:113]
	v_mfma_f32_16x16x32_bf16 v[106:109], v[174:177], v[190:193], v[106:109]
	v_mfma_f32_16x16x32_bf16 v[94:97], v[166:169], v[198:201], v[94:97]
	v_mfma_f32_16x16x32_bf16 v[90:93], v[174:177], v[198:201], v[90:93]
	v_mfma_f32_16x16x32_bf16 v[78:81], v[166:169], v[212:215], v[78:81]
	v_mfma_f32_16x16x32_bf16 v[74:77], v[174:177], v[212:215], v[74:77]
	s_setprio 0
	s_barrier
	s_add_i32 s12, s12, s83
	s_mov_b32 m0, s12
	ds_read_b128 v[178:181], v156 offset:16384
	ds_read_b128 v[182:185], v156 offset:17408
	ds_read_b128 v[186:189], v156 offset:18432
	ds_read_b128 v[190:193], v156 offset:19456
	ds_read_b128 v[194:197], v156 offset:20480
	ds_read_b128 v[198:201], v156 offset:21504
	ds_read_b128 v[202:205], v156 offset:22528
	ds_read_b128 v[212:215], v156 offset:23552
	global_load_lds_dwordx4 v0, s[46:47]
	s_add_i32 m0, s12, 0x2000
	s_add_u32 s34, s46, 0x40000
	s_addc_u32 s35, s47, 0
	s_add_i32 s12, s14, s83
	global_load_lds_dwordx4 v142, s[46:47]
	s_mov_b32 m0, s12
	s_nop 0
	global_load_lds_dwordx4 v0, s[34:35]
	s_add_i32 m0, s12, 0x2000
	s_nop 0
	global_load_lds_dwordx4 v142, s[34:35]
	s_mov_b32 m0, s84
	s_nop 0
	global_load_lds_dwordx4 v138, s[48:49]
	s_mov_b32 m0, s85
	s_nop 0
	global_load_lds_dwordx4 v140, s[48:49]
	s_waitcnt vmcnt(8)
	s_waitcnt lgkmcnt(0)
	s_barrier
	s_setprio 1
	s_waitcnt lgkmcnt(0)
	v_mfma_f32_16x16x32_bf16 v[70:73], v[30:33], v[178:181], v[70:73]
	v_mfma_f32_16x16x32_bf16 v[66:69], v[150:153], v[178:181], v[66:69]
	v_mfma_f32_16x16x32_bf16 v[54:57], v[30:33], v[186:189], v[54:57]
	v_mfma_f32_16x16x32_bf16 v[50:53], v[150:153], v[186:189], v[50:53]
	v_mfma_f32_16x16x32_bf16 v[34:37], v[30:33], v[194:197], v[34:37]
	v_mfma_f32_16x16x32_bf16 v[26:29], v[150:153], v[194:197], v[26:29]
	v_mfma_f32_16x16x32_bf16 v[14:17], v[30:33], v[202:205], v[14:17]
	v_mfma_f32_16x16x32_bf16 v[10:13], v[150:153], v[202:205], v[10:13]
	v_mfma_f32_16x16x32_bf16 v[70:73], v[38:41], v[182:185], v[70:73]
	v_mfma_f32_16x16x32_bf16 v[66:69], v[158:161], v[182:185], v[66:69]
	v_mfma_f32_16x16x32_bf16 v[54:57], v[38:41], v[190:193], v[54:57]
	v_mfma_f32_16x16x32_bf16 v[50:53], v[158:161], v[190:193], v[50:53]
	v_mfma_f32_16x16x32_bf16 v[34:37], v[38:41], v[198:201], v[34:37]
	v_mfma_f32_16x16x32_bf16 v[26:29], v[158:161], v[198:201], v[26:29]
	v_mfma_f32_16x16x32_bf16 v[14:17], v[38:41], v[212:215], v[14:17]
	v_mfma_f32_16x16x32_bf16 v[10:13], v[158:161], v[212:215], v[10:13]
	s_setprio 0
	s_setprio 1
	v_mfma_f32_16x16x32_bf16 v[46:49], v[162:165], v[186:189], v[46:49]
	v_mfma_f32_16x16x32_bf16 v[42:45], v[170:173], v[186:189], v[42:45]
	v_mfma_f32_16x16x32_bf16 v[22:25], v[162:165], v[194:197], v[22:25]
	v_mfma_f32_16x16x32_bf16 v[18:21], v[170:173], v[194:197], v[18:21]
	v_mfma_f32_16x16x32_bf16 v[6:9], v[162:165], v[202:205], v[6:9]
	v_mfma_f32_16x16x32_bf16 v[2:5], v[170:173], v[202:205], v[2:5]
	v_mfma_f32_16x16x32_bf16 v[30:33], v[162:165], v[178:181], v[62:65]
	v_mfma_f32_16x16x32_bf16 v[38:41], v[170:173], v[178:181], v[58:61]
	v_mfma_f32_16x16x32_bf16 v[46:49], v[166:169], v[190:193], v[46:49]
	v_mfma_f32_16x16x32_bf16 v[42:45], v[174:177], v[190:193], v[42:45]
	v_mfma_f32_16x16x32_bf16 v[22:25], v[166:169], v[198:201], v[22:25]
	v_mfma_f32_16x16x32_bf16 v[18:21], v[174:177], v[198:201], v[18:21]
	v_mfma_f32_16x16x32_bf16 v[6:9], v[166:169], v[212:215], v[6:9]
	v_mfma_f32_16x16x32_bf16 v[2:5], v[174:177], v[212:215], v[2:5]
	v_mfma_f32_16x16x32_bf16 v[30:33], v[166:169], v[182:185], v[30:33]
	v_mfma_f32_16x16x32_bf16 v[38:41], v[174:177], v[182:185], v[38:41]
	s_setprio 0
	s_barrier
; #define PG8_STAGE(bufoff, gbase, voff) do { _Pragma("unroll") for (int _i = 0; _i < 2; ++_i) \
;         __builtin_amdgcn_global_load_lds((const unsigned*)((const char*)(gbase) + (voff)[_i]), (LAS unsigned*)(lds + (bufoff) + ldsw + _i * 8192), 16, 0, 0); } while (0)
; #define PG8_LDA(dst, b, h) do { _Pragma("unroll") for (int m = 0; m < 4; ++m) _Pragma("unroll") for (int k = 0; k < 2; ++k) dst[m][k] = *(const LAS bf16x8*)(lds + PG8_SA(b, h) + aoff + m * 2048 + k * 1024); } while (0)
; #define PG8_LDB(dst, b, h) do { _Pragma("unroll") for (int n = 0; n < 2; ++n) _Pragma("unroll") for (int k = 0; k < 2; ++k) dst[n][k] = *(const LAS bf16x8*)(lds + PG8_SB(b, h) + boff + n * 2048 + k * 1024); } while (0)
; #define PG8_MMA(ai, bj, At, Bt) do { __builtin_amdgcn_s_setprio(1); _Pragma("unroll") for (int m = 0; m < 4; ++m) _Pragma("unroll") for (int n = 0; n < 2; ++n) _Pragma("unroll") for (int k = 0; k < 2; ++k) \
;         acc[ai][bj][m][n] = __builtin_amdgcn_mfma_f32_16x16x32_bf16(Bt[n][k], At[m][k], acc[ai][bj][m][n], 0, 0, 0); __builtin_amdgcn_s_setprio(0); } while (0)
; #define PG8_WAIT_V(n) asm volatile("s_waitcnt vmcnt(" #n ")" ::: "memory")
; #define PG8_WAIT_L(n) asm volatile("s_waitcnt lgkmcnt(" #n ")" ::: "memory")
; #define PG8_BAR __builtin_amdgcn_s_barrier()
; #define PG8_SCHED __builtin_amdgcn_sched_barrier(0)
; template <class Epi, class Sched>
; __device__ __forceinline__ void gemm_phase(LAS unsigned char* lds, const Gemm g, const Sched& S, const Epi& E, int wid_) {
;     ...
;             PG8_LDB(B0, 1, 0); PG8_LDB(B1, 1, 1); PG8_SCHED; PG8_LDA(At, 1, 0); PG8_STAGE(PG8_SA(0, 1), a2 + hstepA, voffA);
;             PG8_WAIT_V(8); PG8_WAIT_L(0); PG8_BAR; PG8_MMA(0, 0, At, B0); PG8_MMA(0, 1, At, B1); PG8_BAR; PG8_SCHED;
;             PG8_LDA(At, 1, 1); PG8_STAGE(PG8_SB(1, 0), b3, voffB); PG8_STAGE(PG8_SB(1, 1), b3 + hstepB, voffB); PG8_STAGE(PG8_SA(1, 0), a3, voffA);
;             PG8_WAIT_V(8); PG8_WAIT_L(0); PG8_BAR; PG8_MMA(1, 0, At, B0); PG8_MMA(1, 1, At, B1); PG8_BAR; PG8_SCHED;
;         }
	s_add_i32 s12, 0, 0x18000
	v_add_u32_e32 v148, s12, v149
	s_add_i32 s14, 0, 0x1c000
	ds_read_b128 v[58:61], v148
	ds_read_b128 v[62:65], v148 offset:1024
	ds_read_b128 v[150:153], v148 offset:2048
	ds_read_b128 v[158:161], v148 offset:3072
	v_add_u32_e32 v148, s14, v149
	ds_read_b128 v[162:165], v148
	ds_read_b128 v[166:169], v148 offset:1024
	ds_read_b128 v[170:173], v148 offset:2048
	ds_read_b128 v[174:177], v148 offset:3072
	s_add_u32 s34, s48, 0x40000
	s_addc_u32 s35, s49, 0
	s_mov_b32 m0, s89
	ds_read_b128 v[178:181], v156 offset:32768
	ds_read_b128 v[182:185], v156 offset:33792
	ds_read_b128 v[186:189], v156 offset:34816
	ds_read_b128 v[190:193], v156 offset:35840
	ds_read_b128 v[194:197], v156 offset:36864
	ds_read_b128 v[198:201], v156 offset:37888
	ds_read_b128 v[202:205], v156 offset:38912
	ds_read_b128 v[212:215], v156 offset:39936
	global_load_lds_dwordx4 v138, s[34:35]
	s_mov_b32 m0, s57
	s_nop 0
	global_load_lds_dwordx4 v140, s[34:35]
	s_waitcnt vmcnt(8)
	s_waitcnt lgkmcnt(0)
	s_barrier
	s_setprio 1
	s_waitcnt lgkmcnt(0)
	v_mfma_f32_16x16x32_bf16 v[134:137], v[58:61], v[178:181], v[134:137]
	v_mfma_f32_16x16x32_bf16 v[130:133], v[150:153], v[178:181], v[130:133]
	v_mfma_f32_16x16x32_bf16 v[118:121], v[58:61], v[186:189], v[118:121]
	v_mfma_f32_16x16x32_bf16 v[114:117], v[150:153], v[186:189], v[114:117]
	v_mfma_f32_16x16x32_bf16 v[102:105], v[58:61], v[194:197], v[102:105]
	v_mfma_f32_16x16x32_bf16 v[98:101], v[150:153], v[194:197], v[98:101]
	v_mfma_f32_16x16x32_bf16 v[86:89], v[58:61], v[202:205], v[86:89]
	v_mfma_f32_16x16x32_bf16 v[82:85], v[150:153], v[202:205], v[82:85]
	v_mfma_f32_16x16x32_bf16 v[134:137], v[62:65], v[182:185], v[134:137]
	v_mfma_f32_16x16x32_bf16 v[130:133], v[158:161], v[182:185], v[130:133]
	v_mfma_f32_16x16x32_bf16 v[118:121], v[62:65], v[190:193], v[118:121]
	v_mfma_f32_16x16x32_bf16 v[114:117], v[158:161], v[190:193], v[114:117]
	v_mfma_f32_16x16x32_bf16 v[102:105], v[62:65], v[198:201], v[102:105]
	v_mfma_f32_16x16x32_bf16 v[98:101], v[158:161], v[198:201], v[98:101]
	v_mfma_f32_16x16x32_bf16 v[86:89], v[62:65], v[212:215], v[86:89]
	v_mfma_f32_16x16x32_bf16 v[82:85], v[158:161], v[212:215], v[82:85]
	s_setprio 0
	s_setprio 1
	v_mfma_f32_16x16x32_bf16 v[126:129], v[162:165], v[178:181], v[126:129]
	v_mfma_f32_16x16x32_bf16 v[122:125], v[170:173], v[178:181], v[122:125]
	v_mfma_f32_16x16x32_bf16 v[110:113], v[162:165], v[186:189], v[110:113]
	v_mfma_f32_16x16x32_bf16 v[106:109], v[170:173], v[186:189], v[106:109]
	v_mfma_f32_16x16x32_bf16 v[94:97], v[162:165], v[194:197], v[94:97]
	v_mfma_f32_16x16x32_bf16 v[90:93], v[170:173], v[194:197], v[90:93]
	v_mfma_f32_16x16x32_bf16 v[78:81], v[162:165], v[202:205], v[78:81]
	v_mfma_f32_16x16x32_bf16 v[74:77], v[170:173], v[202:205], v[74:77]
	v_mfma_f32_16x16x32_bf16 v[126:129], v[166:169], v[182:185], v[126:129]
	v_mfma_f32_16x16x32_bf16 v[122:125], v[174:177], v[182:185], v[122:125]
	v_mfma_f32_16x16x32_bf16 v[110:113], v[166:169], v[190:193], v[110:113]
	v_mfma_f32_16x16x32_bf16 v[106:109], v[174:177], v[190:193], v[106:109]
	v_mfma_f32_16x16x32_bf16 v[94:97], v[166:169], v[198:201], v[94:97]
	v_mfma_f32_16x16x32_bf16 v[90:93], v[174:177], v[198:201], v[90:93]
	v_mfma_f32_16x16x32_bf16 v[78:81], v[166:169], v[212:215], v[78:81]
	v_mfma_f32_16x16x32_bf16 v[74:77], v[174:177], v[212:215], v[74:77]
	s_setprio 0
	s_barrier
	s_add_i32 s12, s12, s83
	s_add_u32 s100, s46, s70
	s_addc_u32 s101, s47, s71
	s_mov_b32 m0, s12
	ds_read_b128 v[178:181], v156 offset:49152
	ds_read_b128 v[182:185], v156 offset:50176
	ds_read_b128 v[186:189], v156 offset:51200
	ds_read_b128 v[190:193], v156 offset:52224
	ds_read_b128 v[194:197], v156 offset:53248
	ds_read_b128 v[198:201], v156 offset:54272
	ds_read_b128 v[202:205], v156 offset:55296
	ds_read_b128 v[212:215], v156 offset:56320
	global_load_lds_dwordx4 v0, s[100:101]
	s_add_i32 m0, s12, 0x2000
	s_add_u32 s34, s46, 0x40080
	s_addc_u32 s35, s47, 0
	s_add_i32 s12, s14, s83
	global_load_lds_dwordx4 v142, s[100:101]
	s_mov_b32 m0, s12
	s_nop 0
	global_load_lds_dwordx4 v0, s[34:35]
	s_add_i32 m0, s12, 0x2000
	s_nop 0
	global_load_lds_dwordx4 v142, s[34:35]
	s_add_u32 s100, s48, s70
	s_addc_u32 s101, s49, s71
	s_mov_b32 m0, s68
	s_nop 0
	global_load_lds_dwordx4 v138, s[100:101]
	s_mov_b32 m0, s69
	s_nop 0
	global_load_lds_dwordx4 v140, s[100:101]
	s_waitcnt vmcnt(8)
	s_waitcnt lgkmcnt(0)
	s_barrier
	s_setprio 1
	s_waitcnt lgkmcnt(0)
	v_mfma_f32_16x16x32_bf16 v[70:73], v[58:61], v[178:181], v[70:73]
	v_mfma_f32_16x16x32_bf16 v[66:69], v[150:153], v[178:181], v[66:69]
	v_mfma_f32_16x16x32_bf16 v[54:57], v[58:61], v[186:189], v[54:57]
	v_mfma_f32_16x16x32_bf16 v[50:53], v[150:153], v[186:189], v[50:53]
	v_mfma_f32_16x16x32_bf16 v[34:37], v[58:61], v[194:197], v[34:37]
	v_mfma_f32_16x16x32_bf16 v[26:29], v[150:153], v[194:197], v[26:29]
	v_mfma_f32_16x16x32_bf16 v[14:17], v[58:61], v[202:205], v[14:17]
	v_mfma_f32_16x16x32_bf16 v[10:13], v[150:153], v[202:205], v[10:13]
	v_mfma_f32_16x16x32_bf16 v[70:73], v[62:65], v[182:185], v[70:73]
	v_mfma_f32_16x16x32_bf16 v[66:69], v[158:161], v[182:185], v[66:69]
	v_mfma_f32_16x16x32_bf16 v[54:57], v[62:65], v[190:193], v[54:57]
	v_mfma_f32_16x16x32_bf16 v[50:53], v[158:161], v[190:193], v[50:53]
	v_mfma_f32_16x16x32_bf16 v[34:37], v[62:65], v[198:201], v[34:37]
	v_mfma_f32_16x16x32_bf16 v[26:29], v[158:161], v[198:201], v[26:29]
	v_mfma_f32_16x16x32_bf16 v[14:17], v[62:65], v[212:215], v[14:17]
	v_mfma_f32_16x16x32_bf16 v[10:13], v[158:161], v[212:215], v[10:13]
	s_setprio 0
	s_setprio 1
	v_mfma_f32_16x16x32_bf16 v[30:33], v[162:165], v[178:181], v[30:33]
	v_mfma_f32_16x16x32_bf16 v[62:65], v[166:169], v[182:185], v[30:33]
	v_mfma_f32_16x16x32_bf16 v[30:33], v[170:173], v[178:181], v[38:41]
	v_mfma_f32_16x16x32_bf16 v[58:61], v[174:177], v[182:185], v[30:33]
	v_mfma_f32_16x16x32_bf16 v[30:33], v[162:165], v[186:189], v[46:49]
	v_mfma_f32_16x16x32_bf16 v[46:49], v[166:169], v[190:193], v[30:33]
	v_mfma_f32_16x16x32_bf16 v[30:33], v[170:173], v[186:189], v[42:45]
	v_mfma_f32_16x16x32_bf16 v[22:25], v[162:165], v[194:197], v[22:25]
	v_mfma_f32_16x16x32_bf16 v[18:21], v[170:173], v[194:197], v[18:21]
	v_mfma_f32_16x16x32_bf16 v[6:9], v[162:165], v[202:205], v[6:9]
	v_mfma_f32_16x16x32_bf16 v[2:5], v[170:173], v[202:205], v[2:5]
	v_mfma_f32_16x16x32_bf16 v[42:45], v[174:177], v[190:193], v[30:33]
	v_mfma_f32_16x16x32_bf16 v[22:25], v[166:169], v[198:201], v[22:25]
	v_mfma_f32_16x16x32_bf16 v[18:21], v[174:177], v[198:201], v[18:21]
	v_mfma_f32_16x16x32_bf16 v[6:9], v[166:169], v[212:215], v[6:9]
	v_mfma_f32_16x16x32_bf16 v[2:5], v[174:177], v[212:215], v[2:5]
	s_setprio 0
	s_barrier
	s_add_i32 s33, s33, 2
	s_add_u32 s44, s44, 0x100
	s_addc_u32 s45, s45, 0
	s_add_u32 s93, s93, 0x100
	s_addc_u32 s54, s54, 0
	s_cmp_gt_u32 s33, 13
	s_cbranch_scc0 .LBB0_856
	s_and_b64 vcc, exec, s[26:27]
	s_cbranch_vccz .LBB0_859
	s_barrier

; #define PG8_STAGE(bufoff, gbase, voff) do { _Pragma("unroll") for (int _i = 0; _i < 2; ++_i) \
;         __builtin_amdgcn_global_load_lds((const unsigned*)((const char*)(gbase) + (voff)[_i]), (LAS unsigned*)(lds + (bufoff) + ldsw + _i * 8192), 16, 0, 0); } while (0)
; #define PG8_LDA(dst, b, h) do { _Pragma("unroll") for (int m = 0; m < 4; ++m) _Pragma("unroll") for (int k = 0; k < 2; ++k) dst[m][k] = *(const LAS bf16x8*)(lds + PG8_SA(b, h) + aoff + m * 2048 + k * 1024); } while (0)
; #define PG8_LDB(dst, b, h) do { _Pragma("unroll") for (int n = 0; n < 2; ++n) _Pragma("unroll") for (int k = 0; k < 2; ++k) dst[n][k] = *(const LAS bf16x8*)(lds + PG8_SB(b, h) + boff + n * 2048 + k * 1024); } while (0)
; #define PG8_MMA(ai, bj, At, Bt) do { __builtin_amdgcn_s_setprio(1); _Pragma("unroll") for (int m = 0; m < 4; ++m) _Pragma("unroll") for (int n = 0; n < 2; ++n) _Pragma("unroll") for (int k = 0; k < 2; ++k) \
;         acc[ai][bj][m][n] = __builtin_amdgcn_mfma_f32_16x16x32_bf16(Bt[n][k], At[m][k], acc[ai][bj][m][n], 0, 0, 0); __builtin_amdgcn_s_setprio(0); } while (0)
; #define PG8_WAIT_V(n) asm volatile("s_waitcnt vmcnt(" #n ")" ::: "memory")
; #define PG8_WAIT_L(n) asm volatile("s_waitcnt lgkmcnt(" #n ")" ::: "memory")
; #define PG8_BAR __builtin_amdgcn_s_barrier()
; #define PG8_SCHED __builtin_amdgcn_sched_barrier(0)
; template <class Epi, class Sched>
; __device__ __forceinline__ void gemm_phase(LAS unsigned char* lds, const Gemm g, const Sched& S, const Epi& E, int wid_) {
;     ...
;             const bool last = (t == nt - 2);
;             const char* a1 = cA + (size_t)(t + 1) * kstep;
;             const char* a2 = last ? nA : cA + (size_t)(t + 2) * kstep; const char* b2 = last ? nB : cB + (size_t)(t + 2) * kstep;
;             const char* a3 = a2 + kstep; const char* b3 = b2 + kstep;
;             PG8_LDB(B0, 0, 0); PG8_LDB(B1, 0, 1); PG8_SCHED; PG8_LDA(At, 0, 0); PG8_STAGE(PG8_SA(1, 1), a1 + hstepA, voffA);
;             PG8_WAIT_V(8); PG8_WAIT_L(0); PG8_BAR; PG8_MMA(0, 0, At, B0); PG8_MMA(0, 1, At, B1); PG8_BAR; PG8_SCHED;
;             PG8_LDA(At, 0, 1); PG8_STAGE(PG8_SB(0, 0), b2, voffB); PG8_STAGE(PG8_SB(0, 1), b2 + hstepB, voffB); PG8_STAGE(PG8_SA(0, 0), a2, voffA);
;             PG8_WAIT_V(8); PG8_WAIT_L(0); PG8_BAR; PG8_MMA(1, 0, At, B0); PG8_MMA(1, 1, At, B1); PG8_BAR; PG8_SCHED;
.LBB0_908:
	s_add_u32 s12, s38, 0xfffc0080
	s_addc_u32 s14, s39, -1
	s_add_i32 s34, 0, 0x10000
	s_cmp_eq_u32 s33, 12
	s_cselect_b32 s43, s19, s14
	s_cselect_b32 s42, s21, s12
	s_cselect_b32 s41, s82, s54
	s_cselect_b32 s40, s83, s84
	s_add_i32 s12, 0, 0x14000
	v_add_u32_e32 v142, s34, v160
	v_add_u32_e32 v170, s12, v160
	ds_read_b128 v[130:133], v142
	ds_read_b128 v[134:137], v142 offset:1024
	ds_read_b128 v[138:141], v142 offset:2048
	ds_read_b128 v[142:145], v142 offset:3072
	ds_read_b128 v[156:159], v170
	ds_read_b128 v[162:165], v170 offset:1024
	ds_read_b128 v[166:169], v170 offset:2048
	ds_read_b128 v[170:173], v170 offset:3072
	s_add_i32 m0, s46, 0xc000
	ds_read_b128 v[174:177], v161
	ds_read_b128 v[178:181], v161 offset:1024
	ds_read_b128 v[182:185], v161 offset:2048
	ds_read_b128 v[186:189], v161 offset:3072
	ds_read_b128 v[190:193], v161 offset:4096
	ds_read_b128 v[194:197], v161 offset:5120
	ds_read_b128 v[198:201], v161 offset:6144
	ds_read_b128 v[202:205], v161 offset:7168
	global_load_lds_dwordx4 v152, s[38:39]
	s_add_i32 m0, s46, 0xe000
	s_nop 0
	global_load_lds_dwordx4 v154, s[38:39]
	s_waitcnt vmcnt(8)
	s_waitcnt lgkmcnt(0)
	s_barrier
	s_setprio 1
	s_waitcnt lgkmcnt(0)
	v_mfma_f32_16x16x32_bf16 v[126:129], v[130:133], v[174:177], v[126:129]
	v_mfma_f32_16x16x32_bf16 v[122:125], v[138:141], v[174:177], v[122:125]
	v_mfma_f32_16x16x32_bf16 v[118:121], v[130:133], v[182:185], v[118:121]
	v_mfma_f32_16x16x32_bf16 v[110:113], v[138:141], v[182:185], v[110:113]
	v_mfma_f32_16x16x32_bf16 v[102:105], v[130:133], v[190:193], v[102:105]
	v_mfma_f32_16x16x32_bf16 v[94:97], v[138:141], v[190:193], v[94:97]
	v_mfma_f32_16x16x32_bf16 v[86:89], v[130:133], v[198:201], v[86:89]
	v_mfma_f32_16x16x32_bf16 v[78:81], v[138:141], v[198:201], v[78:81]
	v_mfma_f32_16x16x32_bf16 v[126:129], v[134:137], v[178:181], v[126:129]
	v_mfma_f32_16x16x32_bf16 v[122:125], v[142:145], v[178:181], v[122:125]
	v_mfma_f32_16x16x32_bf16 v[118:121], v[134:137], v[186:189], v[118:121]
	v_mfma_f32_16x16x32_bf16 v[110:113], v[142:145], v[186:189], v[110:113]
	v_mfma_f32_16x16x32_bf16 v[102:105], v[134:137], v[194:197], v[102:105]
	v_mfma_f32_16x16x32_bf16 v[94:97], v[142:145], v[194:197], v[94:97]
	v_mfma_f32_16x16x32_bf16 v[86:89], v[134:137], v[202:205], v[86:89]
	v_mfma_f32_16x16x32_bf16 v[78:81], v[142:145], v[202:205], v[78:81]
	s_setprio 0
	s_setprio 1
	v_mfma_f32_16x16x32_bf16 v[114:117], v[156:159], v[174:177], v[114:117]
	v_mfma_f32_16x16x32_bf16 v[106:109], v[166:169], v[174:177], v[106:109]
	v_mfma_f32_16x16x32_bf16 v[98:101], v[156:159], v[182:185], v[98:101]
	v_mfma_f32_16x16x32_bf16 v[90:93], v[166:169], v[182:185], v[90:93]
	v_mfma_f32_16x16x32_bf16 v[82:85], v[156:159], v[190:193], v[82:85]
	v_mfma_f32_16x16x32_bf16 v[74:77], v[166:169], v[190:193], v[74:77]
	v_mfma_f32_16x16x32_bf16 v[70:73], v[156:159], v[198:201], v[70:73]
	v_mfma_f32_16x16x32_bf16 v[66:69], v[166:169], v[198:201], v[66:69]
	v_mfma_f32_16x16x32_bf16 v[114:117], v[162:165], v[178:181], v[114:117]
	v_mfma_f32_16x16x32_bf16 v[106:109], v[170:173], v[178:181], v[106:109]
	v_mfma_f32_16x16x32_bf16 v[98:101], v[162:165], v[186:189], v[98:101]
	v_mfma_f32_16x16x32_bf16 v[90:93], v[170:173], v[186:189], v[90:93]
	v_mfma_f32_16x16x32_bf16 v[82:85], v[162:165], v[194:197], v[82:85]
	v_mfma_f32_16x16x32_bf16 v[74:77], v[170:173], v[194:197], v[74:77]
	v_mfma_f32_16x16x32_bf16 v[70:73], v[162:165], v[202:205], v[70:73]
	v_mfma_f32_16x16x32_bf16 v[66:69], v[170:173], v[202:205], v[66:69]
	s_setprio 0
	s_barrier
	s_add_i32 s14, s34, s37
	s_mov_b32 m0, s14
	ds_read_b128 v[174:177], v161 offset:16384
	ds_read_b128 v[178:181], v161 offset:17408
	ds_read_b128 v[182:185], v161 offset:18432
	ds_read_b128 v[186:189], v161 offset:19456
	ds_read_b128 v[190:193], v161 offset:20480
	ds_read_b128 v[194:197], v161 offset:21504
	ds_read_b128 v[198:201], v161 offset:22528
	ds_read_b128 v[202:205], v161 offset:23552
	global_load_lds_dwordx4 v0, s[40:41]
	s_add_i32 m0, s14, 0x2000
	s_add_u32 s34, s40, 0x40000
	s_addc_u32 s35, s41, 0
	s_add_i32 s12, s12, s37
	global_load_lds_dwordx4 v150, s[40:41]
	s_mov_b32 m0, s12
	s_nop 0
	global_load_lds_dwordx4 v0, s[34:35]
	s_add_i32 m0, s12, 0x2000
	s_nop 0
	global_load_lds_dwordx4 v150, s[34:35]
	s_mov_b32 m0, s46
	s_nop 0
	global_load_lds_dwordx4 v146, s[42:43]
	s_mov_b32 m0, s47
	s_nop 0
	global_load_lds_dwordx4 v148, s[42:43]
	s_waitcnt vmcnt(8)
	s_waitcnt lgkmcnt(0)
	s_barrier
	s_setprio 1
	s_waitcnt lgkmcnt(0)
	v_mfma_f32_16x16x32_bf16 v[62:65], v[130:133], v[174:177], v[62:65]
	v_mfma_f32_16x16x32_bf16 v[58:61], v[138:141], v[174:177], v[58:61]
	v_mfma_f32_16x16x32_bf16 v[54:57], v[130:133], v[182:185], v[54:57]
	v_mfma_f32_16x16x32_bf16 v[46:49], v[138:141], v[182:185], v[46:49]
	v_mfma_f32_16x16x32_bf16 v[38:41], v[130:133], v[190:193], v[38:41]
	v_mfma_f32_16x16x32_bf16 v[30:33], v[138:141], v[190:193], v[30:33]
	v_mfma_f32_16x16x32_bf16 v[22:25], v[130:133], v[198:201], v[22:25]
	v_mfma_f32_16x16x32_bf16 v[14:17], v[138:141], v[198:201], v[14:17]
	v_mfma_f32_16x16x32_bf16 v[62:65], v[134:137], v[178:181], v[62:65]
	v_mfma_f32_16x16x32_bf16 v[58:61], v[142:145], v[178:181], v[58:61]
	v_mfma_f32_16x16x32_bf16 v[54:57], v[134:137], v[186:189], v[54:57]
	v_mfma_f32_16x16x32_bf16 v[46:49], v[142:145], v[186:189], v[46:49]
	v_mfma_f32_16x16x32_bf16 v[38:41], v[134:137], v[194:197], v[38:41]
	v_mfma_f32_16x16x32_bf16 v[30:33], v[142:145], v[194:197], v[30:33]
	v_mfma_f32_16x16x32_bf16 v[22:25], v[134:137], v[202:205], v[22:25]
	v_mfma_f32_16x16x32_bf16 v[14:17], v[142:145], v[202:205], v[14:17]
	s_setprio 0
	s_setprio 1
	v_mfma_f32_16x16x32_bf16 v[50:53], v[156:159], v[174:177], v[50:53]
	v_mfma_f32_16x16x32_bf16 v[42:45], v[166:169], v[174:177], v[42:45]
	v_mfma_f32_16x16x32_bf16 v[34:37], v[156:159], v[182:185], v[34:37]
	v_mfma_f32_16x16x32_bf16 v[26:29], v[166:169], v[182:185], v[26:29]
	v_mfma_f32_16x16x32_bf16 v[18:21], v[156:159], v[190:193], v[18:21]
	v_mfma_f32_16x16x32_bf16 v[10:13], v[166:169], v[190:193], v[10:13]
	v_mfma_f32_16x16x32_bf16 v[6:9], v[156:159], v[198:201], v[6:9]
	v_mfma_f32_16x16x32_bf16 v[2:5], v[166:169], v[198:201], v[2:5]
	v_mfma_f32_16x16x32_bf16 v[50:53], v[162:165], v[178:181], v[50:53]
	v_mfma_f32_16x16x32_bf16 v[42:45], v[170:173], v[178:181], v[42:45]
	v_mfma_f32_16x16x32_bf16 v[34:37], v[162:165], v[186:189], v[34:37]
	v_mfma_f32_16x16x32_bf16 v[26:29], v[170:173], v[186:189], v[26:29]
	v_mfma_f32_16x16x32_bf16 v[18:21], v[162:165], v[194:197], v[18:21]
	v_mfma_f32_16x16x32_bf16 v[10:13], v[170:173], v[194:197], v[10:13]
	v_mfma_f32_16x16x32_bf16 v[6:9], v[162:165], v[202:205], v[6:9]
	v_mfma_f32_16x16x32_bf16 v[2:5], v[170:173], v[202:205], v[2:5]
	s_setprio 0
	s_barrier
; #define PG8_STAGE(bufoff, gbase, voff) do { _Pragma("unroll") for (int _i = 0; _i < 2; ++_i) \
;         __builtin_amdgcn_global_load_lds((const unsigned*)((const char*)(gbase) + (voff)[_i]), (LAS unsigned*)(lds + (bufoff) + ldsw + _i * 8192), 16, 0, 0); } while (0)
; #define PG8_LDA(dst, b, h) do { _Pragma("unroll") for (int m = 0; m < 4; ++m) _Pragma("unroll") for (int k = 0; k < 2; ++k) dst[m][k] = *(const LAS bf16x8*)(lds + PG8_SA(b, h) + aoff + m * 2048 + k * 1024); } while (0)
; #define PG8_LDB(dst, b, h) do { _Pragma("unroll") for (int n = 0; n < 2; ++n) _Pragma("unroll") for (int k = 0; k < 2; ++k) dst[n][k] = *(const LAS bf16x8*)(lds + PG8_SB(b, h) + boff + n * 2048 + k * 1024); } while (0)
; #define PG8_MMA(ai, bj, At, Bt) do { __builtin_amdgcn_s_setprio(1); _Pragma("unroll") for (int m = 0; m < 4; ++m) _Pragma("unroll") for (int n = 0; n < 2; ++n) _Pragma("unroll") for (int k = 0; k < 2; ++k) \
;         acc[ai][bj][m][n] = __builtin_amdgcn_mfma_f32_16x16x32_bf16(Bt[n][k], At[m][k], acc[ai][bj][m][n], 0, 0, 0); __builtin_amdgcn_s_setprio(0); } while (0)
; #define PG8_WAIT_V(n) asm volatile("s_waitcnt vmcnt(" #n ")" ::: "memory")
; #define PG8_WAIT_L(n) asm volatile("s_waitcnt lgkmcnt(" #n ")" ::: "memory")
; #define PG8_BAR __builtin_amdgcn_s_barrier()
; #define PG8_SCHED __builtin_amdgcn_sched_barrier(0)
; template <class Epi, class Sched>
; __device__ __forceinline__ void gemm_phase(LAS unsigned char* lds, const Gemm g, const Sched& S, const Epi& E, int wid_) {
;     ...
;             PG8_LDB(B0, 1, 0); PG8_LDB(B1, 1, 1); PG8_SCHED; PG8_LDA(At, 1, 0); PG8_STAGE(PG8_SA(0, 1), a2 + hstepA, voffA);
;             PG8_WAIT_V(8); PG8_WAIT_L(0); PG8_BAR; PG8_MMA(0, 0, At, B0); PG8_MMA(0, 1, At, B1); PG8_BAR; PG8_SCHED;
;             PG8_LDA(At, 1, 1); PG8_STAGE(PG8_SB(1, 0), b3, voffB); PG8_STAGE(PG8_SB(1, 1), b3 + hstepB, voffB); PG8_STAGE(PG8_SA(1, 0), a3, voffA);
;             PG8_WAIT_V(8); PG8_WAIT_L(0); PG8_BAR; PG8_MMA(1, 0, At, B0); PG8_MMA(1, 1, At, B1); PG8_BAR; PG8_SCHED;
;         }
	s_add_i32 s12, 0, 0x18000
	s_add_i32 s14, 0, 0x1c000
	v_add_u32_e32 v142, s12, v160
	v_add_u32_e32 v170, s14, v160
	ds_read_b128 v[130:133], v142
	ds_read_b128 v[134:137], v142 offset:1024
	ds_read_b128 v[138:141], v142 offset:2048
	ds_read_b128 v[142:145], v142 offset:3072
	ds_read_b128 v[156:159], v170
	ds_read_b128 v[162:165], v170 offset:1024
	ds_read_b128 v[166:169], v170 offset:2048
	ds_read_b128 v[170:173], v170 offset:3072
	s_add_u32 s34, s42, 0x40000
	s_addc_u32 s35, s43, 0
	s_mov_b32 m0, s48
	ds_read_b128 v[174:177], v161 offset:32768
	ds_read_b128 v[178:181], v161 offset:33792
	ds_read_b128 v[182:185], v161 offset:34816
	ds_read_b128 v[186:189], v161 offset:35840
	ds_read_b128 v[190:193], v161 offset:36864
	ds_read_b128 v[194:197], v161 offset:37888
	ds_read_b128 v[198:201], v161 offset:38912
	ds_read_b128 v[202:205], v161 offset:39936
	global_load_lds_dwordx4 v146, s[34:35]
	s_mov_b32 m0, s49
	s_nop 0
	global_load_lds_dwordx4 v148, s[34:35]
	s_waitcnt vmcnt(8)
	s_waitcnt lgkmcnt(0)
	s_barrier
	s_setprio 1
	s_waitcnt lgkmcnt(0)
	v_mfma_f32_16x16x32_bf16 v[126:129], v[130:133], v[174:177], v[126:129]
	v_mfma_f32_16x16x32_bf16 v[122:125], v[138:141], v[174:177], v[122:125]
	v_mfma_f32_16x16x32_bf16 v[118:121], v[130:133], v[182:185], v[118:121]
	v_mfma_f32_16x16x32_bf16 v[110:113], v[138:141], v[182:185], v[110:113]
	v_mfma_f32_16x16x32_bf16 v[102:105], v[130:133], v[190:193], v[102:105]
	v_mfma_f32_16x16x32_bf16 v[94:97], v[138:141], v[190:193], v[94:97]
	v_mfma_f32_16x16x32_bf16 v[86:89], v[130:133], v[198:201], v[86:89]
	v_mfma_f32_16x16x32_bf16 v[78:81], v[138:141], v[198:201], v[78:81]
	v_mfma_f32_16x16x32_bf16 v[126:129], v[134:137], v[178:181], v[126:129]
	v_mfma_f32_16x16x32_bf16 v[122:125], v[142:145], v[178:181], v[122:125]
	v_mfma_f32_16x16x32_bf16 v[118:121], v[134:137], v[186:189], v[118:121]
	v_mfma_f32_16x16x32_bf16 v[110:113], v[142:145], v[186:189], v[110:113]
	v_mfma_f32_16x16x32_bf16 v[102:105], v[134:137], v[194:197], v[102:105]
	v_mfma_f32_16x16x32_bf16 v[94:97], v[142:145], v[194:197], v[94:97]
	v_mfma_f32_16x16x32_bf16 v[86:89], v[134:137], v[202:205], v[86:89]
	v_mfma_f32_16x16x32_bf16 v[78:81], v[142:145], v[202:205], v[78:81]
	s_setprio 0
	s_setprio 1
	v_mfma_f32_16x16x32_bf16 v[114:117], v[156:159], v[174:177], v[114:117]
	v_mfma_f32_16x16x32_bf16 v[106:109], v[166:169], v[174:177], v[106:109]
	v_mfma_f32_16x16x32_bf16 v[98:101], v[156:159], v[182:185], v[98:101]
	v_mfma_f32_16x16x32_bf16 v[90:93], v[166:169], v[182:185], v[90:93]
	v_mfma_f32_16x16x32_bf16 v[82:85], v[156:159], v[190:193], v[82:85]
	v_mfma_f32_16x16x32_bf16 v[74:77], v[166:169], v[190:193], v[74:77]
	v_mfma_f32_16x16x32_bf16 v[70:73], v[156:159], v[198:201], v[70:73]
	v_mfma_f32_16x16x32_bf16 v[66:69], v[166:169], v[198:201], v[66:69]
	v_mfma_f32_16x16x32_bf16 v[114:117], v[162:165], v[178:181], v[114:117]
	v_mfma_f32_16x16x32_bf16 v[106:109], v[170:173], v[178:181], v[106:109]
	v_mfma_f32_16x16x32_bf16 v[98:101], v[162:165], v[186:189], v[98:101]
	v_mfma_f32_16x16x32_bf16 v[90:93], v[170:173], v[186:189], v[90:93]
	v_mfma_f32_16x16x32_bf16 v[82:85], v[162:165], v[194:197], v[82:85]
	v_mfma_f32_16x16x32_bf16 v[74:77], v[170:173], v[194:197], v[74:77]
	v_mfma_f32_16x16x32_bf16 v[70:73], v[162:165], v[202:205], v[70:73]
	v_mfma_f32_16x16x32_bf16 v[66:69], v[170:173], v[202:205], v[66:69]
	s_setprio 0
	s_barrier
	s_add_i32 s12, s12, s37
	s_add_u32 s100, s40, s70
	s_addc_u32 s101, s41, s71
	s_mov_b32 m0, s12
	ds_read_b128 v[174:177], v161 offset:49152
	ds_read_b128 v[178:181], v161 offset:50176
	ds_read_b128 v[182:185], v161 offset:51200
	ds_read_b128 v[186:189], v161 offset:52224
	ds_read_b128 v[190:193], v161 offset:53248
	ds_read_b128 v[194:197], v161 offset:54272
	ds_read_b128 v[198:201], v161 offset:55296
	ds_read_b128 v[202:205], v161 offset:56320
	global_load_lds_dwordx4 v0, s[100:101]
	s_add_i32 m0, s12, 0x2000
	s_add_u32 s34, s40, 0x40080
	s_addc_u32 s35, s41, 0
	s_add_i32 s12, s14, s37
	global_load_lds_dwordx4 v150, s[100:101]
	s_mov_b32 m0, s12
	s_nop 0
	global_load_lds_dwordx4 v0, s[34:35]
	s_add_i32 m0, s12, 0x2000
	s_nop 0
	global_load_lds_dwordx4 v150, s[34:35]
	s_add_u32 s100, s42, s70
	s_addc_u32 s101, s43, s71
	s_mov_b32 m0, s69
	s_nop 0
	global_load_lds_dwordx4 v146, s[100:101]
	s_mov_b32 m0, s80
	s_nop 0
	global_load_lds_dwordx4 v148, s[100:101]
	s_waitcnt vmcnt(8)
	s_waitcnt lgkmcnt(0)
	s_barrier
	s_setprio 1
	s_waitcnt lgkmcnt(0)
	v_mfma_f32_16x16x32_bf16 v[62:65], v[130:133], v[174:177], v[62:65]
	v_mfma_f32_16x16x32_bf16 v[58:61], v[138:141], v[174:177], v[58:61]
	v_mfma_f32_16x16x32_bf16 v[54:57], v[130:133], v[182:185], v[54:57]
	v_mfma_f32_16x16x32_bf16 v[46:49], v[138:141], v[182:185], v[46:49]
	v_mfma_f32_16x16x32_bf16 v[38:41], v[130:133], v[190:193], v[38:41]
	v_mfma_f32_16x16x32_bf16 v[30:33], v[138:141], v[190:193], v[30:33]
	v_mfma_f32_16x16x32_bf16 v[22:25], v[130:133], v[198:201], v[22:25]
	v_mfma_f32_16x16x32_bf16 v[14:17], v[138:141], v[198:201], v[14:17]
	v_mfma_f32_16x16x32_bf16 v[62:65], v[134:137], v[178:181], v[62:65]
	v_mfma_f32_16x16x32_bf16 v[58:61], v[142:145], v[178:181], v[58:61]
	v_mfma_f32_16x16x32_bf16 v[54:57], v[134:137], v[186:189], v[54:57]
	v_mfma_f32_16x16x32_bf16 v[46:49], v[142:145], v[186:189], v[46:49]
	v_mfma_f32_16x16x32_bf16 v[38:41], v[134:137], v[194:197], v[38:41]
	v_mfma_f32_16x16x32_bf16 v[30:33], v[142:145], v[194:197], v[30:33]
	v_mfma_f32_16x16x32_bf16 v[22:25], v[134:137], v[202:205], v[22:25]
	v_mfma_f32_16x16x32_bf16 v[14:17], v[142:145], v[202:205], v[14:17]
	s_setprio 0
	s_setprio 1
	v_mfma_f32_16x16x32_bf16 v[50:53], v[156:159], v[174:177], v[50:53]
	v_mfma_f32_16x16x32_bf16 v[42:45], v[166:169], v[174:177], v[42:45]
	v_mfma_f32_16x16x32_bf16 v[34:37], v[156:159], v[182:185], v[34:37]
	v_mfma_f32_16x16x32_bf16 v[26:29], v[166:169], v[182:185], v[26:29]
	v_mfma_f32_16x16x32_bf16 v[18:21], v[156:159], v[190:193], v[18:21]
	v_mfma_f32_16x16x32_bf16 v[10:13], v[166:169], v[190:193], v[10:13]
	v_mfma_f32_16x16x32_bf16 v[6:9], v[156:159], v[198:201], v[6:9]
	v_mfma_f32_16x16x32_bf16 v[2:5], v[166:169], v[198:201], v[2:5]
	v_mfma_f32_16x16x32_bf16 v[50:53], v[162:165], v[178:181], v[50:53]
	v_mfma_f32_16x16x32_bf16 v[42:45], v[170:173], v[178:181], v[42:45]
	v_mfma_f32_16x16x32_bf16 v[34:37], v[162:165], v[186:189], v[34:37]
	v_mfma_f32_16x16x32_bf16 v[26:29], v[170:173], v[186:189], v[26:29]
	v_mfma_f32_16x16x32_bf16 v[18:21], v[162:165], v[194:197], v[18:21]
	v_mfma_f32_16x16x32_bf16 v[10:13], v[170:173], v[194:197], v[10:13]
	v_mfma_f32_16x16x32_bf16 v[6:9], v[162:165], v[202:205], v[6:9]
	v_mfma_f32_16x16x32_bf16 v[2:5], v[170:173], v[202:205], v[2:5]
	s_setprio 0
	s_barrier
	s_add_i32 s33, s33, 2
	s_add_u32 s38, s38, 0x100
	s_addc_u32 s39, s39, 0
	s_add_u32 s84, s84, 0x100
	s_addc_u32 s54, s54, 0
	s_cmp_gt_u32 s33, 13
	s_cbranch_scc0 .LBB0_908
	s_and_b64 vcc, exec, s[8:9]
	s_cbranch_vccz .LBB0_911
	s_barrier
